# w_out/ff2 epilogue: all 8 residual loads of each half issued up front (second-half accumulators parked in this wave's drained LDS stage chunks during the first half), counted vmcnt waits at first use
# speedup vs baseline: 1.0085x; 1.0085x over previous
.LBB0_1054:
	s_add_u32 s10, s30, 0xfffc0080
	s_addc_u32 s11, s31, -1
	s_add_i32 s50, 0, 0x10000
	v_add_u32_e32 v76, s50, v247
	ds_read_b128 v[64:67], v76
	ds_read_b128 v[68:71], v76 offset:1024
	ds_read_b128 v[72:75], v76 offset:2048
	ds_read_b128 v[76:79], v76 offset:3072
	s_cmp_eq_u32 s39, 12
	s_cselect_b32 s13, s16, s11
	s_cselect_b32 s12, s17, s10
	s_cselect_b32 s11, s20, s37
	s_cselect_b32 s10, s21, s35
	v_lshl_add_u64 v[200:201], s[30:31], 0, v[184:185]
	s_add_i32 m0, s69, 0xc000
	ds_read_b128 v[80:83], v250
	ds_read_b128 v[84:87], v250 offset:1024
	ds_read_b128 v[88:91], v250 offset:2048
	ds_read_b128 v[92:95], v250 offset:3072
	ds_read_b128 v[160:163], v250 offset:4096
	ds_read_b128 v[188:191], v250 offset:5120
	ds_read_b128 v[192:195], v250 offset:6144
	ds_read_b128 v[196:199], v250 offset:7168
	global_load_lds_dwordx4 v[200:201], off
	v_lshl_add_u64 v[200:201], s[30:31], 0, v[186:187]
	s_add_i32 m0, s69, 0xe000
	s_nop 0
	global_load_lds_dwordx4 v[200:201], off
	s_waitcnt lgkmcnt(8)
	s_barrier
	s_waitcnt lgkmcnt(0)
	s_setprio 1
	s_waitcnt lgkmcnt(0)
	v_mfma_f32_16x16x32_bf16 v[156:159], v[64:67], v[80:83], v[156:159]
	v_mfma_f32_16x16x32_bf16 v[152:155], v[72:75], v[80:83], v[152:155]
	v_mfma_f32_16x16x32_bf16 v[148:151], v[64:67], v[88:91], v[148:151]
	v_mfma_f32_16x16x32_bf16 v[144:147], v[72:75], v[88:91], v[144:147]
	v_mfma_f32_16x16x32_bf16 v[140:143], v[64:67], v[160:163], v[140:143]
	v_mfma_f32_16x16x32_bf16 v[136:139], v[72:75], v[160:163], v[136:139]
	v_mfma_f32_16x16x32_bf16 v[132:135], v[64:67], v[192:195], v[132:135]
	v_mfma_f32_16x16x32_bf16 v[128:131], v[72:75], v[192:195], v[128:131]
	v_mfma_f32_16x16x32_bf16 v[156:159], v[68:71], v[84:87], v[156:159]
	v_mfma_f32_16x16x32_bf16 v[152:155], v[76:79], v[84:87], v[152:155]
	v_mfma_f32_16x16x32_bf16 v[148:151], v[68:71], v[92:95], v[148:151]
	v_mfma_f32_16x16x32_bf16 v[144:147], v[76:79], v[92:95], v[144:147]
	v_mfma_f32_16x16x32_bf16 v[140:143], v[68:71], v[188:191], v[140:143]
	v_mfma_f32_16x16x32_bf16 v[136:139], v[76:79], v[188:191], v[136:139]
	v_mfma_f32_16x16x32_bf16 v[132:135], v[68:71], v[196:199], v[132:135]
	v_mfma_f32_16x16x32_bf16 v[128:131], v[76:79], v[196:199], v[128:131]
	s_setprio 0
	s_barrier
	s_add_i32 s54, 0, 0x14000
	s_add_i32 s50, s50, s58
	v_add_u32_e32 v168, s54, v247
	v_lshl_add_u64 v[224:225], s[10:11], 0, v[174:175]
	s_mov_b32 m0, s50
	ds_read_b128 v[200:203], v168
	ds_read_b128 v[204:207], v168 offset:1024
	ds_read_b128 v[208:211], v168 offset:2048
	ds_read_b128 v[212:215], v168 offset:3072
	global_load_lds_dwordx4 v[224:225], off
	v_lshl_add_u64 v[226:227], s[10:11], 0, v[164:165]
	s_add_i32 m0, s50, 0x2000
	s_nop 0
	global_load_lds_dwordx4 v[226:227], off
	s_barrier
	s_waitcnt lgkmcnt(0)
	s_setprio 1
	s_waitcnt lgkmcnt(0)
	v_mfma_f32_16x16x32_bf16 v[124:127], v[200:203], v[80:83], v[124:127]
	v_mfma_f32_16x16x32_bf16 v[80:83], v[208:211], v[80:83], v[120:123]
	v_mfma_f32_16x16x32_bf16 v[124:127], v[204:207], v[84:87], v[124:127]
	v_mfma_f32_16x16x32_bf16 v[80:83], v[212:215], v[84:87], v[80:83]
	v_mfma_f32_16x16x32_bf16 v[84:87], v[200:203], v[88:91], v[116:119]
	v_mfma_f32_16x16x32_bf16 v[88:91], v[208:211], v[88:91], v[112:115]
	v_mfma_f32_16x16x32_bf16 v[104:107], v[208:211], v[160:163], v[104:107]
	v_mfma_f32_16x16x32_bf16 v[100:103], v[200:203], v[192:195], v[100:103]
	v_mfma_f32_16x16x32_bf16 v[96:99], v[208:211], v[192:195], v[96:99]
	v_mfma_f32_16x16x32_bf16 v[84:87], v[204:207], v[92:95], v[84:87]
	v_mfma_f32_16x16x32_bf16 v[88:91], v[212:215], v[92:95], v[88:91]
	v_mfma_f32_16x16x32_bf16 v[92:95], v[200:203], v[160:163], v[108:111]
	v_mfma_f32_16x16x32_bf16 v[104:107], v[212:215], v[188:191], v[104:107]
	v_mfma_f32_16x16x32_bf16 v[100:103], v[204:207], v[196:199], v[100:103]
	v_mfma_f32_16x16x32_bf16 v[96:99], v[212:215], v[196:199], v[96:99]
	v_mfma_f32_16x16x32_bf16 v[92:95], v[204:207], v[188:191], v[92:95]
	s_setprio 0
	s_mov_b32 m0, s69
	v_lshl_add_u64 v[228:229], s[12:13], 0, v[182:183]
	s_barrier
	ds_read_b128 v[108:111], v250 offset:16384
	ds_read_b128 v[112:115], v250 offset:17408
	ds_read_b128 v[116:119], v250 offset:18432
	ds_read_b128 v[120:123], v250 offset:19456
	ds_read_b128 v[160:163], v250 offset:20480
	ds_read_b128 v[188:191], v250 offset:21504
	ds_read_b128 v[192:195], v250 offset:22528
	ds_read_b128 v[196:199], v250 offset:23552
	global_load_lds_dwordx4 v[228:229], off
	v_lshl_add_u64 v[230:231], s[12:13], 0, v[166:167]
	s_mov_b32 m0, s75
	s_nop 0
	global_load_lds_dwordx4 v[230:231], off
	s_barrier
	s_waitcnt lgkmcnt(0)
	s_setprio 1
	s_waitcnt lgkmcnt(0)
	v_mfma_f32_16x16x32_bf16 v[60:63], v[64:67], v[108:111], v[60:63]
	v_mfma_f32_16x16x32_bf16 v[56:59], v[72:75], v[108:111], v[56:59]
	v_mfma_f32_16x16x32_bf16 v[52:55], v[64:67], v[116:119], v[52:55]
	v_mfma_f32_16x16x32_bf16 v[48:51], v[72:75], v[116:119], v[48:51]
	v_mfma_f32_16x16x32_bf16 v[44:47], v[64:67], v[160:163], v[44:47]
	v_mfma_f32_16x16x32_bf16 v[40:43], v[72:75], v[160:163], v[40:43]
	v_mfma_f32_16x16x32_bf16 v[36:39], v[64:67], v[192:195], v[36:39]
	v_mfma_f32_16x16x32_bf16 v[32:35], v[72:75], v[192:195], v[32:35]
	v_mfma_f32_16x16x32_bf16 v[60:63], v[68:71], v[112:115], v[60:63]
	v_mfma_f32_16x16x32_bf16 v[56:59], v[76:79], v[112:115], v[56:59]
	v_mfma_f32_16x16x32_bf16 v[52:55], v[68:71], v[120:123], v[52:55]
	v_mfma_f32_16x16x32_bf16 v[48:51], v[76:79], v[120:123], v[48:51]
	v_mfma_f32_16x16x32_bf16 v[44:47], v[68:71], v[188:191], v[44:47]
	v_mfma_f32_16x16x32_bf16 v[40:43], v[76:79], v[188:191], v[40:43]
	v_mfma_f32_16x16x32_bf16 v[36:39], v[68:71], v[196:199], v[36:39]
	v_mfma_f32_16x16x32_bf16 v[32:35], v[76:79], v[196:199], v[32:35]
	s_setprio 0
	s_barrier
	s_add_u32 s50, s10, 0x40000
	s_addc_u32 s51, s11, 0
	s_add_i32 s54, s54, s58
	v_lshl_add_u64 v[64:65], s[50:51], 0, v[174:175]
	s_mov_b32 m0, s54
	s_nop 0
	global_load_lds_dwordx4 v[64:65], off
	v_lshl_add_u64 v[64:65], s[50:51], 0, v[164:165]
	s_add_i32 m0, s54, 0x2000
	s_nop 0
	global_load_lds_dwordx4 v[64:65], off
	s_waitcnt vmcnt(6)
	s_barrier
	s_setprio 1
	v_mfma_f32_16x16x32_bf16 v[28:31], v[200:203], v[108:111], v[28:31]
	v_mfma_f32_16x16x32_bf16 v[24:27], v[208:211], v[108:111], v[24:27]
	v_mfma_f32_16x16x32_bf16 v[20:23], v[200:203], v[116:119], v[20:23]
	v_mfma_f32_16x16x32_bf16 v[16:19], v[208:211], v[116:119], v[16:19]
	v_mfma_f32_16x16x32_bf16 v[12:15], v[200:203], v[160:163], v[12:15]
	v_mfma_f32_16x16x32_bf16 v[8:11], v[208:211], v[160:163], v[8:11]
	v_mfma_f32_16x16x32_bf16 v[4:7], v[200:203], v[192:195], v[4:7]
	v_mfma_f32_16x16x32_bf16 v[0:3], v[208:211], v[192:195], v[0:3]
	v_mfma_f32_16x16x32_bf16 v[28:31], v[204:207], v[112:115], v[28:31]
	v_mfma_f32_16x16x32_bf16 v[24:27], v[212:215], v[112:115], v[24:27]
	v_mfma_f32_16x16x32_bf16 v[20:23], v[204:207], v[120:123], v[20:23]
	v_mfma_f32_16x16x32_bf16 v[16:19], v[212:215], v[120:123], v[16:19]
	v_mfma_f32_16x16x32_bf16 v[12:15], v[204:207], v[188:191], v[12:15]
	v_mfma_f32_16x16x32_bf16 v[8:11], v[212:215], v[188:191], v[8:11]
	v_mfma_f32_16x16x32_bf16 v[4:7], v[204:207], v[196:199], v[4:7]
	v_mfma_f32_16x16x32_bf16 v[0:3], v[212:215], v[196:199], v[0:3]
	s_setprio 0
	s_add_i32 s50, 0, 0x18000
	v_add_u32_e32 v76, s50, v247
	s_barrier
	ds_read_b128 v[64:67], v76
	ds_read_b128 v[68:71], v76 offset:1024
	ds_read_b128 v[72:75], v76 offset:2048
	ds_read_b128 v[76:79], v76 offset:3072
	s_add_u32 s12, s12, 0x40000
	s_addc_u32 s13, s13, 0
	s_mov_b32 m0, s76
	v_lshl_add_u64 v[116:117], s[12:13], 0, v[182:183]
	ds_read_b128 v[108:111], v250 offset:32768
	ds_read_b128 v[112:115], v250 offset:33792
	ds_read_b128 v[160:163], v250 offset:34816
	ds_read_b128 v[188:191], v250 offset:35840
	ds_read_b128 v[192:195], v250 offset:36864
	ds_read_b128 v[196:199], v250 offset:37888
	ds_read_b128 v[200:203], v250 offset:38912
	ds_read_b128 v[204:207], v250 offset:39936
	global_load_lds_dwordx4 v[116:117], off
	v_lshl_add_u64 v[116:117], s[12:13], 0, v[166:167]
	s_mov_b32 m0, s77
	s_nop 0
	global_load_lds_dwordx4 v[116:117], off
	s_waitcnt lgkmcnt(8)
	s_barrier
	s_waitcnt lgkmcnt(0)
	s_setprio 1
	s_waitcnt lgkmcnt(0)
	v_mfma_f32_16x16x32_bf16 v[116:119], v[64:67], v[108:111], v[156:159]
	v_mfma_f32_16x16x32_bf16 v[156:159], v[68:71], v[112:115], v[116:119]
	v_mfma_f32_16x16x32_bf16 v[116:119], v[72:75], v[108:111], v[152:155]
	v_mfma_f32_16x16x32_bf16 v[152:155], v[76:79], v[112:115], v[116:119]
	v_mfma_f32_16x16x32_bf16 v[116:119], v[64:67], v[160:163], v[148:151]
	v_mfma_f32_16x16x32_bf16 v[148:151], v[68:71], v[188:191], v[116:119]
	v_mfma_f32_16x16x32_bf16 v[116:119], v[72:75], v[160:163], v[144:147]
	v_mfma_f32_16x16x32_bf16 v[144:147], v[76:79], v[188:191], v[116:119]
	v_mfma_f32_16x16x32_bf16 v[116:119], v[64:67], v[192:195], v[140:143]
	v_mfma_f32_16x16x32_bf16 v[140:143], v[68:71], v[196:199], v[116:119]
	v_mfma_f32_16x16x32_bf16 v[116:119], v[72:75], v[192:195], v[136:139]
	v_mfma_f32_16x16x32_bf16 v[136:139], v[76:79], v[196:199], v[116:119]
	v_mfma_f32_16x16x32_bf16 v[116:119], v[64:67], v[200:203], v[132:135]
	v_mfma_f32_16x16x32_bf16 v[132:135], v[68:71], v[204:207], v[116:119]
	v_mfma_f32_16x16x32_bf16 v[116:119], v[72:75], v[200:203], v[128:131]
	v_mfma_f32_16x16x32_bf16 v[128:131], v[76:79], v[204:207], v[116:119]
	s_setprio 0
	s_barrier
	s_add_i32 s12, 0, 0x1c000
	s_nop 3
	v_add_u32_e32 v116, s12, v247
	s_add_i32 s13, s50, s58
	ds_read_b128 v[208:211], v116
	ds_read_b128 v[212:215], v116 offset:1024
	ds_read_b128 v[216:219], v116 offset:2048
	ds_read_b128 v[220:223], v116 offset:3072
	v_lshl_add_u64 v[116:117], v[224:225], 0, s[8:9]
	s_mov_b32 m0, s13
	s_nop 0
	global_load_lds_dwordx4 v[116:117], off
	v_lshl_add_u64 v[116:117], v[226:227], 0, s[8:9]
	s_add_i32 m0, s13, 0x2000
	s_nop 0
	global_load_lds_dwordx4 v[116:117], off
	s_barrier
	s_waitcnt lgkmcnt(0)
	s_setprio 1
	s_waitcnt lgkmcnt(0)
	v_mfma_f32_16x16x32_bf16 v[80:83], v[216:219], v[108:111], v[80:83]
	v_mfma_f32_16x16x32_bf16 v[116:119], v[208:211], v[108:111], v[124:127]
	v_mfma_f32_16x16x32_bf16 v[120:123], v[220:223], v[112:115], v[80:83]
	v_mfma_f32_16x16x32_bf16 v[80:83], v[208:211], v[160:163], v[84:87]
	v_mfma_f32_16x16x32_bf16 v[124:127], v[212:215], v[112:115], v[116:119]
	v_mfma_f32_16x16x32_bf16 v[116:119], v[212:215], v[188:191], v[80:83]
	v_mfma_f32_16x16x32_bf16 v[80:83], v[216:219], v[160:163], v[88:91]
	v_mfma_f32_16x16x32_bf16 v[112:115], v[220:223], v[188:191], v[80:83]
	v_mfma_f32_16x16x32_bf16 v[80:83], v[208:211], v[192:195], v[92:95]
	v_mfma_f32_16x16x32_bf16 v[108:111], v[212:215], v[196:199], v[80:83]
	v_mfma_f32_16x16x32_bf16 v[80:83], v[216:219], v[192:195], v[104:107]
	v_mfma_f32_16x16x32_bf16 v[104:107], v[220:223], v[196:199], v[80:83]
	v_mfma_f32_16x16x32_bf16 v[80:83], v[208:211], v[200:203], v[100:103]
	v_mfma_f32_16x16x32_bf16 v[100:103], v[212:215], v[204:207], v[80:83]
	v_mfma_f32_16x16x32_bf16 v[80:83], v[216:219], v[200:203], v[96:99]
	v_mfma_f32_16x16x32_bf16 v[96:99], v[220:223], v[204:207], v[80:83]
	s_setprio 0
	s_mov_b32 m0, s78
	v_lshl_add_u64 v[200:201], v[228:229], 0, s[8:9]
	s_barrier
	s_nop 2
	ds_read_b128 v[80:83], v250 offset:49152
	ds_read_b128 v[84:87], v250 offset:50176
	ds_read_b128 v[88:91], v250 offset:51200
	ds_read_b128 v[92:95], v250 offset:52224
	ds_read_b128 v[160:163], v250 offset:53248
	ds_read_b128 v[188:191], v250 offset:54272
	ds_read_b128 v[192:195], v250 offset:55296
	ds_read_b128 v[196:199], v250 offset:56320
	global_load_lds_dwordx4 v[200:201], off
	v_lshl_add_u64 v[200:201], v[230:231], 0, s[8:9]
	s_mov_b32 m0, s79
	s_nop 0
	global_load_lds_dwordx4 v[200:201], off
	s_barrier
	s_waitcnt lgkmcnt(0)
	s_setprio 1
	s_waitcnt lgkmcnt(0)
	v_mfma_f32_16x16x32_bf16 v[60:63], v[64:67], v[80:83], v[60:63]
	v_mfma_f32_16x16x32_bf16 v[56:59], v[72:75], v[80:83], v[56:59]
	v_mfma_f32_16x16x32_bf16 v[52:55], v[64:67], v[88:91], v[52:55]
	v_mfma_f32_16x16x32_bf16 v[48:51], v[72:75], v[88:91], v[48:51]
	v_mfma_f32_16x16x32_bf16 v[44:47], v[64:67], v[160:163], v[44:47]
	v_mfma_f32_16x16x32_bf16 v[40:43], v[72:75], v[160:163], v[40:43]
	v_mfma_f32_16x16x32_bf16 v[36:39], v[64:67], v[192:195], v[36:39]
	v_mfma_f32_16x16x32_bf16 v[32:35], v[72:75], v[192:195], v[32:35]
	v_mfma_f32_16x16x32_bf16 v[60:63], v[68:71], v[84:87], v[60:63]
	v_mfma_f32_16x16x32_bf16 v[56:59], v[76:79], v[84:87], v[56:59]
	v_mfma_f32_16x16x32_bf16 v[52:55], v[68:71], v[92:95], v[52:55]
	v_mfma_f32_16x16x32_bf16 v[48:51], v[76:79], v[92:95], v[48:51]
	v_mfma_f32_16x16x32_bf16 v[44:47], v[68:71], v[188:191], v[44:47]
	v_mfma_f32_16x16x32_bf16 v[40:43], v[76:79], v[188:191], v[40:43]
	v_mfma_f32_16x16x32_bf16 v[36:39], v[68:71], v[196:199], v[36:39]
	v_mfma_f32_16x16x32_bf16 v[32:35], v[76:79], v[196:199], v[32:35]
	s_setprio 0
	s_barrier
	s_add_u32 s10, s10, 0x40080
	s_addc_u32 s11, s11, 0
	s_add_i32 s12, s12, s58
	v_lshl_add_u64 v[64:65], s[10:11], 0, v[174:175]
	s_mov_b32 m0, s12
	s_nop 0
	global_load_lds_dwordx4 v[64:65], off
	v_lshl_add_u64 v[64:65], s[10:11], 0, v[164:165]
	s_add_i32 m0, s12, 0x2000
	s_nop 0
	global_load_lds_dwordx4 v[64:65], off
	s_waitcnt vmcnt(6)
	s_barrier
	s_setprio 1
	v_mfma_f32_16x16x32_bf16 v[28:31], v[208:211], v[80:83], v[28:31]
	v_mfma_f32_16x16x32_bf16 v[24:27], v[216:219], v[80:83], v[24:27]
	v_mfma_f32_16x16x32_bf16 v[20:23], v[208:211], v[88:91], v[20:23]
	v_mfma_f32_16x16x32_bf16 v[16:19], v[216:219], v[88:91], v[16:19]
	v_mfma_f32_16x16x32_bf16 v[12:15], v[208:211], v[160:163], v[12:15]
	v_mfma_f32_16x16x32_bf16 v[8:11], v[216:219], v[160:163], v[8:11]
	v_mfma_f32_16x16x32_bf16 v[4:7], v[208:211], v[192:195], v[4:7]
	v_mfma_f32_16x16x32_bf16 v[0:3], v[216:219], v[192:195], v[0:3]
	v_mfma_f32_16x16x32_bf16 v[28:31], v[212:215], v[84:87], v[28:31]
	v_mfma_f32_16x16x32_bf16 v[24:27], v[220:223], v[84:87], v[24:27]
	v_mfma_f32_16x16x32_bf16 v[20:23], v[212:215], v[92:95], v[20:23]
	v_mfma_f32_16x16x32_bf16 v[16:19], v[220:223], v[92:95], v[16:19]
	v_mfma_f32_16x16x32_bf16 v[12:15], v[212:215], v[188:191], v[12:15]
	v_mfma_f32_16x16x32_bf16 v[8:11], v[220:223], v[188:191], v[8:11]
	v_mfma_f32_16x16x32_bf16 v[4:7], v[212:215], v[196:199], v[4:7]
	v_mfma_f32_16x16x32_bf16 v[0:3], v[220:223], v[196:199], v[0:3]
	s_setprio 0
	s_add_i32 s39, s39, 2
	s_add_u32 s30, s30, 0x100
	s_addc_u32 s31, s31, 0
	s_add_u32 s35, s35, 0x100
	s_addc_u32 s37, s37, 0
	s_cmp_gt_u32 s39, 13
	s_barrier
	s_cbranch_scc0 .LBB0_1054
	s_nop 15
	s_nop 15
	s_waitcnt vmcnt(6)
	v_lshl_add_u32 v64, v237, 4, s58
	v_add_u32_e32 v65, 0x10000, v64
	ds_write_b128 v64, v[0:3] offset:49152
	ds_write_b128 v64, v[4:7] offset:57344
	ds_write_b128 v65, v[8:11]
	ds_write_b128 v65, v[12:15] offset:8192
	ds_write_b128 v64, v[16:19]
	ds_write_b128 v64, v[20:23] offset:8192
	ds_write_b128 v65, v[24:27] offset:16384
	ds_write_b128 v65, v[28:31] offset:24576
	s_mov_b64 s[10:11], s[0:1]
	s_load_dwordx4 s[92:95], s[10:11], 0xb8
	s_nop 0
	s_load_dwordx2 s[10:11], s[10:11], 0xd0
	v_lshl_or_b32 v192, s24, 8, v248
	v_ashrrev_i32_e32 v193, 31, v192
	v_lshlrev_b64 v[64:65], 2, v[192:193]
	s_mov_b32 s12, s42
	s_waitcnt lgkmcnt(0)
	v_lshl_add_u64 v[68:69], s[92:93], 0, v[64:65]
	v_lshl_add_u64 v[76:77], s[94:95], 0, v[64:65]
	global_load_dwordx4 v[80:83], v[68:69], off offset:16
	global_load_dwordx4 v[88:91], v[68:69], off
	global_load_dwordx4 v[84:87], v[76:77], off offset:16
	global_load_dwordx4 v[92:95], v[76:77], off
	global_load_dwordx4 v[64:67], v[68:69], off offset:528
	global_load_dwordx4 v[72:75], v[68:69], off offset:512
	s_nop 0
	global_load_dwordx4 v[68:71], v[76:77], off offset:528
	s_nop 0
	global_load_dwordx4 v[76:79], v[76:77], off offset:512
	s_cmp_eq_u32 s12, 0
	s_cselect_b64 s[30:31], -1, 0
	s_cmp_lg_u32 s12, 0
	s_cselect_b64 s[12:13], -1, 0
	s_lshl_b32 s16, s34, 11
	v_mov_b32_e32 v206, 1.0
	v_mov_b32_e32 v204, 0
	s_and_b64 vcc, exec, s[30:31]
	v_add_u32_e32 v251, s16, v249
	v_mov_b32_e32 v208, 0
	v_mov_b32_e32 v210, 1.0
	s_cbranch_vccnz .LBB0_1057
	ds_read_b64 v[208:209], v251
	s_waitcnt lgkmcnt(0)
	v_mov_b32_e32 v210, v209

.LBB0_1063:
	v_lshl_add_u32 v188, s25, 8, v246
	s_add_u32 s54, s10, 0x2a00000
	v_ashrrev_i32_e32 v189, 31, v188
	s_addc_u32 s55, s11, 0
	v_lshlrev_b64 v[216:217], 11, v[188:189]
	v_lshl_add_u64 v[220:221], s[54:55], 0, v[216:217]
	v_lshlrev_b64 v[160:161], 1, v[192:193]
	v_lshl_add_u64 v[226:227], v[220:221], 0, v[160:161]
	s_waitcnt lgkmcnt(0)
	s_mov_b32 s101, 0
	s_mov_b32 s100, 0x8000
	v_lshl_add_u64 v[162:163], v[226:227], 0, s[100:101]
	s_mov_b32 s100, 0x10000
	v_lshl_add_u64 v[168:169], v[226:227], 0, s[100:101]
	s_mov_b32 s100, 0x18000
	v_lshl_add_u64 v[172:173], v[226:227], 0, s[100:101]
	global_load_dwordx4 v[0:3], v[226:227], off
	global_load_dwordx4 v[4:7], v[162:163], off
	global_load_dwordx4 v[8:11], v[168:169], off
	global_load_dwordx4 v[12:15], v[172:173], off
	global_load_dwordx4 v[16:19], v[226:227], off offset:256
	global_load_dwordx4 v[20:23], v[162:163], off offset:256
	global_load_dwordx4 v[24:27], v[168:169], off offset:256
	global_load_dwordx4 v[28:31], v[172:173], off offset:256
	v_or_b32_e32 v194, 16, v188
	v_ashrrev_i32_e32 v195, 31, v194
	v_lshl_add_u64 v[190:191], s[54:55], 0, v[160:161]
	v_lshlrev_b64 v[224:225], 11, v[194:195]
	v_lshl_add_u64 v[230:231], v[190:191], 0, v[224:225]
	v_lshl_add_u64 v[216:217], v[190:191], 0, v[216:217]
	v_or_b32_e32 v222, 0x80, v192
	v_ashrrev_i32_e32 v223, 31, v222
	s_lshl_b32 s12, s24, 3
	s_or_b32 s12, s12, s80
	s_ashr_i32 s13, s12, 31
	s_lshl_b64 s[12:13], s[12:13], 2
	s_add_u32 s10, s10, s12
	s_addc_u32 s11, s11, s13
	s_add_u32 s50, s10, 0xeb80000
	s_addc_u32 s51, s11, 0
	s_waitcnt vmcnt(7)
	s_nop 1
	v_mov_b32_e32 v198, v0
	v_mov_b32_e32 v199, v1
	v_mov_b32_e32 v200, v2
	v_mov_b32_e32 v201, v3
	v_lshlrev_b32_e32 v168, 16, v198
	v_and_b32_e32 v169, 0xffff0000, v198
	v_lshlrev_b32_e32 v172, 16, v199
	v_and_b32_e32 v173, 0xffff0000, v199
	v_sub_f32_e32 v199, v173, v208
	v_sub_f32_e32 v198, v172, v208
	v_sub_f32_e32 v213, v169, v208
	v_sub_f32_e32 v212, v168, v208
	v_pk_mul_f32 v[212:213], v[210:211], v[212:213] op_sel_hi:[0,1]
	v_pk_mul_f32 v[198:199], v[210:211], v[198:199] op_sel_hi:[0,1]
	v_pk_fma_f32 v[198:199], v[90:91], v[198:199], v[94:95]
	v_pk_fma_f32 v[212:213], v[88:89], v[212:213], v[92:93]
	v_cndmask_b32_e64 v199, v199, v173, s[30:31]
	v_cndmask_b32_e64 v213, v213, v169, s[30:31]
	v_cndmask_b32_e64 v212, v212, v168, s[30:31]
	v_cndmask_b32_e64 v198, v198, v172, s[30:31]
	v_lshlrev_b32_e32 v168, 16, v200
	v_and_b32_e32 v169, 0xffff0000, v200
	v_lshlrev_b32_e32 v172, 16, v201
	v_and_b32_e32 v173, 0xffff0000, v201
	v_pk_fma_f32 v[218:219], v[198:199], s[70:71], v[158:159] op_sel_hi:[1,0,1]
	v_pk_fma_f32 v[228:229], v[212:213], s[70:71], v[156:157] op_sel_hi:[1,0,1]
	v_sub_f32_e32 v157, v173, v208
	v_sub_f32_e32 v156, v172, v208
	v_sub_f32_e32 v159, v169, v208
	v_sub_f32_e32 v158, v168, v208
	v_pk_mul_f32 v[158:159], v[210:211], v[158:159] op_sel_hi:[0,1]
	v_pk_mul_f32 v[156:157], v[210:211], v[156:157] op_sel_hi:[0,1]
	v_pk_fma_f32 v[156:157], v[82:83], v[156:157], v[86:87]
	v_pk_fma_f32 v[158:159], v[80:81], v[158:159], v[84:85]
	v_cndmask_b32_e64 v157, v157, v173, s[30:31]
	v_cndmask_b32_e64 v159, v159, v169, s[30:31]
	v_cndmask_b32_e64 v158, v158, v168, s[30:31]
	v_cndmask_b32_e64 v156, v156, v172, s[30:31]
	v_pk_fma_f32 v[232:233], v[156:157], s[70:71], v[154:155] op_sel_hi:[1,0,1]
	v_pk_fma_f32 v[154:155], v[158:159], s[70:71], v[152:153] op_sel_hi:[1,0,1]
	v_cvt_pk_bf16_f32 v152, v228, v229
	v_cvt_pk_bf16_f32 v153, v218, v219
	s_waitcnt vmcnt(6)
	s_nop 1
	v_mov_b32_e32 v160, v4
	v_mov_b32_e32 v161, v5
	v_mov_b32_e32 v162, v6
	v_mov_b32_e32 v163, v7
	v_lshlrev_b32_e32 v157, 16, v160
	v_add_f32_e32 v156, v154, v155
	v_mul_f32_e32 v205, v154, v154
	v_mul_f32_e32 v207, v155, v155
	v_cvt_pk_bf16_f32 v154, v154, v155
	v_cvt_pk_bf16_f32 v155, v232, v233
	global_store_dwordx4 v[216:217], v[152:155], off
	v_or_b32_e32 v216, 32, v188
	v_ashrrev_i32_e32 v217, 31, v216
	v_and_b32_e32 v159, 0xffff0000, v160
	v_lshlrev_b32_e32 v168, 16, v161
	v_and_b32_e32 v169, 0xffff0000, v161
	v_add_f32_e32 v198, v228, v229
	v_add_f32_e32 v200, v218, v219
	v_mul_f32_e32 v213, v228, v228
	v_mul_f32_e32 v215, v229, v229
	v_mul_f32_e32 v209, v218, v218
	v_mul_f32_e32 v211, v219, v219
	v_lshlrev_b64 v[228:229], 11, v[216:217]
	v_sub_f32_e32 v161, v169, v204
	v_sub_f32_e32 v160, v168, v204
	v_sub_f32_e32 v219, v159, v204
	v_sub_f32_e32 v218, v157, v204
	v_lshl_add_u64 v[234:235], v[190:191], 0, v[228:229]
	v_pk_mul_f32 v[218:219], v[206:207], v[218:219] op_sel_hi:[0,1]
	v_pk_mul_f32 v[160:161], v[206:207], v[160:161] op_sel_hi:[0,1]
	v_pk_fma_f32 v[160:161], v[90:91], v[160:161], v[94:95]
	v_pk_fma_f32 v[218:219], v[88:89], v[218:219], v[92:93]
	v_cndmask_b32_e64 v161, v161, v169, s[30:31]
	v_cndmask_b32_e64 v219, v219, v159, s[30:31]
	v_cndmask_b32_e64 v218, v218, v157, s[30:31]
	v_cndmask_b32_e64 v160, v160, v168, s[30:31]
	v_lshlrev_b32_e32 v168, 16, v163
	v_and_b32_e32 v169, 0xffff0000, v163
	v_pk_fma_f32 v[150:151], v[160:161], s[70:71], v[150:151] op_sel_hi:[1,0,1]
	v_pk_fma_f32 v[160:161], v[218:219], s[70:71], v[148:149] op_sel_hi:[1,0,1]
	v_lshlrev_b32_e32 v157, 16, v162
	v_and_b32_e32 v159, 0xffff0000, v162
	v_sub_f32_e32 v149, v169, v204
	v_sub_f32_e32 v148, v168, v204
	v_sub_f32_e32 v163, v159, v204
	v_sub_f32_e32 v162, v157, v204
	v_pk_mul_f32 v[148:149], v[206:207], v[148:149] op_sel_hi:[0,1]
	v_pk_mul_f32 v[162:163], v[206:207], v[162:163] op_sel_hi:[0,1]
	v_pk_fma_f32 v[148:149], v[82:83], v[148:149], v[86:87]
	v_pk_fma_f32 v[162:163], v[80:81], v[162:163], v[84:85]
	v_cndmask_b32_e64 v149, v149, v169, s[30:31]
	v_cndmask_b32_e64 v148, v148, v168, s[30:31]
	v_cndmask_b32_e64 v219, v163, v159, s[30:31]
	v_cndmask_b32_e64 v218, v162, v157, s[30:31]
	v_pk_fma_f32 v[162:163], v[148:149], s[70:71], v[146:147] op_sel_hi:[1,0,1]
	v_or_b32_e32 v148, 48, v188
	v_ashrrev_i32_e32 v149, 31, v148
	v_pk_fma_f32 v[218:219], v[218:219], s[70:71], v[144:145] op_sel_hi:[1,0,1]
	v_cvt_pk_bf16_f32 v144, v160, v161
	v_cvt_pk_bf16_f32 v145, v150, v151
	v_add_f32_e32 v158, v232, v233
	v_cvt_pk_bf16_f32 v146, v218, v219
	v_cvt_pk_bf16_f32 v147, v162, v163
	global_store_dwordx4 v[230:231], v[144:147], off
	v_lshlrev_b64 v[230:231], 11, v[148:149]
	v_mul_f32_e32 v197, v232, v232
	v_mul_f32_e32 v203, v233, v233
	v_lshl_add_u64 v[232:233], v[190:191], 0, v[230:231]
	s_waitcnt vmcnt(7)
	s_nop 1
	v_mov_b32_e32 v152, v8
	v_mov_b32_e32 v153, v9
	v_mov_b32_e32 v154, v10
	v_mov_b32_e32 v155, v11
	v_lshlrev_b32_e32 v157, 16, v152
	v_and_b32_e32 v159, 0xffff0000, v152
	v_lshlrev_b32_e32 v168, 16, v153
	v_and_b32_e32 v169, 0xffff0000, v153
	v_sub_f32_e32 v153, v169, v202
	v_sub_f32_e32 v152, v168, v202
	v_sub_f32_e32 v253, v159, v202
	v_sub_f32_e32 v252, v157, v202
	v_pk_mul_f32 v[252:253], v[178:179], v[252:253] op_sel_hi:[0,1]
	v_pk_mul_f32 v[152:153], v[178:179], v[152:153] op_sel_hi:[0,1]
	v_pk_fma_f32 v[152:153], v[90:91], v[152:153], v[94:95]
	v_pk_fma_f32 v[252:253], v[88:89], v[252:253], v[92:93]
	v_cndmask_b32_e64 v153, v153, v169, s[30:31]
	v_cndmask_b32_e64 v253, v253, v159, s[30:31]
	v_cndmask_b32_e64 v252, v252, v157, s[30:31]
	v_cndmask_b32_e64 v152, v152, v168, s[30:31]
	v_lshlrev_b32_e32 v157, 16, v154
	v_and_b32_e32 v159, 0xffff0000, v154
	v_lshlrev_b32_e32 v168, 16, v155
	v_and_b32_e32 v169, 0xffff0000, v155
	v_pk_fma_f32 v[142:143], v[152:153], s[70:71], v[142:143] op_sel_hi:[1,0,1]
	v_sub_f32_e32 v153, v169, v202
	v_sub_f32_e32 v152, v168, v202
	v_sub_f32_e32 v155, v159, v202
	v_sub_f32_e32 v154, v157, v202
	v_pk_mul_f32 v[154:155], v[178:179], v[154:155] op_sel_hi:[0,1]
	v_pk_mul_f32 v[152:153], v[178:179], v[152:153] op_sel_hi:[0,1]
	v_pk_fma_f32 v[152:153], v[82:83], v[152:153], v[86:87]
	v_pk_fma_f32 v[154:155], v[80:81], v[154:155], v[84:85]
	v_cndmask_b32_e64 v153, v153, v169, s[30:31]
	v_cndmask_b32_e64 v155, v155, v159, s[30:31]
	v_cndmask_b32_e64 v154, v154, v157, s[30:31]
	v_cndmask_b32_e64 v152, v152, v168, s[30:31]
	v_pk_fma_f32 v[140:141], v[252:253], s[70:71], v[140:141] op_sel_hi:[1,0,1]
	v_pk_fma_f32 v[138:139], v[152:153], s[70:71], v[138:139] op_sel_hi:[1,0,1]
	v_pk_fma_f32 v[136:137], v[154:155], s[70:71], v[136:137] op_sel_hi:[1,0,1]
	v_cvt_pk_bf16_f32 v152, v140, v141
	v_cvt_pk_bf16_f32 v153, v142, v143
	s_waitcnt vmcnt(6)
	s_nop 1
	v_mov_b32_e32 v144, v12
	v_mov_b32_e32 v145, v13
	v_mov_b32_e32 v146, v14
	v_mov_b32_e32 v147, v15
	v_lshlrev_b32_e32 v157, 16, v145
	v_cvt_pk_bf16_f32 v154, v136, v137
	v_cvt_pk_bf16_f32 v155, v138, v139
	global_store_dwordx4 v[234:235], v[152:155], off
	v_and_b32_e32 v159, 0xffff0000, v145
	v_sub_f32_e32 v145, v159, v196
	v_lshlrev_b32_e32 v154, 16, v144
	v_and_b32_e32 v155, 0xffff0000, v144
	v_sub_f32_e32 v144, v157, v196
	v_sub_f32_e32 v153, v155, v196
	v_sub_f32_e32 v152, v154, v196
	v_pk_mul_f32 v[152:153], v[176:177], v[152:153] op_sel_hi:[0,1]
	v_pk_mul_f32 v[144:145], v[176:177], v[144:145] op_sel_hi:[0,1]
	v_pk_fma_f32 v[144:145], v[90:91], v[144:145], v[94:95]
	v_pk_fma_f32 v[152:153], v[88:89], v[152:153], v[92:93]
	v_cndmask_b32_e64 v145, v145, v159, s[30:31]
	v_cndmask_b32_e64 v153, v153, v155, s[30:31]
	v_cndmask_b32_e64 v152, v152, v154, s[30:31]
	v_cndmask_b32_e64 v144, v144, v157, s[30:31]
	v_pk_fma_f32 v[134:135], v[144:145], s[70:71], v[134:135] op_sel_hi:[1,0,1]
	v_pk_fma_f32 v[144:145], v[152:153], s[70:71], v[132:133] op_sel_hi:[1,0,1]
	v_lshlrev_b32_e32 v152, 16, v146
	v_and_b32_e32 v153, 0xffff0000, v146
	v_lshlrev_b32_e32 v154, 16, v147
	v_and_b32_e32 v155, 0xffff0000, v147
	v_sub_f32_e32 v133, v155, v196
	v_sub_f32_e32 v132, v154, v196
	v_sub_f32_e32 v147, v153, v196
	v_sub_f32_e32 v146, v152, v196
	v_pk_mul_f32 v[146:147], v[176:177], v[146:147] op_sel_hi:[0,1]
	v_pk_mul_f32 v[132:133], v[176:177], v[132:133] op_sel_hi:[0,1]
	v_pk_fma_f32 v[132:133], v[82:83], v[132:133], v[86:87]
	v_pk_fma_f32 v[146:147], v[80:81], v[146:147], v[84:85]
	v_cndmask_b32_e64 v133, v133, v155, s[30:31]
	v_cndmask_b32_e64 v153, v147, v153, s[30:31]
	v_cndmask_b32_e64 v152, v146, v152, s[30:31]
	v_cndmask_b32_e64 v132, v132, v154, s[30:31]
	v_pk_fma_f32 v[146:147], v[132:133], s[70:71], v[130:131] op_sel_hi:[1,0,1]
	v_pk_fma_f32 v[152:153], v[152:153], s[70:71], v[128:129] op_sel_hi:[1,0,1]
	v_cvt_pk_bf16_f32 v128, v144, v145
	v_cvt_pk_bf16_f32 v129, v134, v135
	v_lshlrev_b64 v[132:133], 1, v[222:223]
	v_cvt_pk_bf16_f32 v130, v152, v153
	v_cvt_pk_bf16_f32 v131, v146, v147
	global_store_dwordx4 v[232:233], v[128:131], off
	v_lshl_add_u64 v[220:221], v[220:221], 0, v[132:133]
	v_lshl_add_u64 v[128:129], s[54:55], 0, v[224:225]
	v_lshl_add_u64 v[226:227], v[128:129], 0, v[132:133]
	s_waitcnt vmcnt(7)
	s_nop 1
	v_mov_b32_e32 v232, v16
	v_mov_b32_e32 v233, v17
	v_mov_b32_e32 v234, v18
	v_mov_b32_e32 v235, v19
	v_lshlrev_b32_e32 v157, 16, v232
	v_and_b32_e32 v159, 0xffff0000, v232
	v_lshlrev_b32_e32 v168, 16, v233
	v_and_b32_e32 v169, 0xffff0000, v233
	v_sub_f32_e32 v155, v169, v208
	v_sub_f32_e32 v154, v168, v208
	v_sub_f32_e32 v223, v159, v208
	v_sub_f32_e32 v222, v157, v208
	v_pk_mul_f32 v[222:223], v[210:211], v[222:223] op_sel_hi:[0,1]
	v_pk_mul_f32 v[154:155], v[210:211], v[154:155] op_sel_hi:[0,1]
	v_pk_fma_f32 v[154:155], v[74:75], v[154:155], v[78:79]
	v_pk_fma_f32 v[222:223], v[72:73], v[222:223], v[76:77]
	v_cndmask_b32_e64 v155, v155, v169, s[30:31]
	v_cndmask_b32_e64 v223, v223, v159, s[30:31]
	v_cndmask_b32_e64 v222, v222, v157, s[30:31]
	v_cndmask_b32_e64 v154, v154, v168, s[30:31]
	v_lshlrev_b32_e32 v157, 16, v234
	v_and_b32_e32 v159, 0xffff0000, v234
	v_lshlrev_b32_e32 v168, 16, v235
	v_and_b32_e32 v169, 0xffff0000, v235
	v_pk_fma_f32 v[126:127], v[154:155], s[70:71], v[126:127] op_sel_hi:[1,0,1]
	v_pk_fma_f32 v[154:155], v[222:223], s[70:71], v[124:125] op_sel_hi:[1,0,1]
	v_sub_f32_e32 v125, v169, v208
	v_sub_f32_e32 v124, v168, v208
	v_sub_f32_e32 v223, v159, v208
	v_sub_f32_e32 v222, v157, v208
	v_pk_mul_f32 v[222:223], v[210:211], v[222:223] op_sel_hi:[0,1]
	v_pk_mul_f32 v[124:125], v[210:211], v[124:125] op_sel_hi:[0,1]
	v_pk_fma_f32 v[124:125], v[66:67], v[124:125], v[70:71]
	v_pk_fma_f32 v[222:223], v[64:65], v[222:223], v[68:69]
	v_cndmask_b32_e64 v125, v125, v169, s[30:31]
	v_cndmask_b32_e64 v225, v223, v159, s[30:31]
	v_cndmask_b32_e64 v224, v222, v157, s[30:31]
	v_cndmask_b32_e64 v124, v124, v168, s[30:31]
	v_pk_fma_f32 v[222:223], v[124:125], s[70:71], v[122:123] op_sel_hi:[1,0,1]
	v_pk_fma_f32 v[224:225], v[224:225], s[70:71], v[120:121] op_sel_hi:[1,0,1]
	v_pk_mul_f32 v[120:121], v[222:223], v[222:223]
	v_pk_mul_f32 v[122:123], v[224:225], v[224:225]
	s_waitcnt vmcnt(6)
	s_nop 1
	v_mov_b32_e32 v128, v20
	v_mov_b32_e32 v129, v21
	v_mov_b32_e32 v130, v22
	v_mov_b32_e32 v131, v23
	v_and_b32_e32 v168, 0xffff0000, v128
	v_pk_mov_b32 v[124:125], v[122:123], v[120:121] op_sel:[1,0]
	v_mov_b32_e32 v123, v121
	v_pk_add_f32 v[120:121], v[124:125], v[122:123]
	v_lshlrev_b32_e32 v169, 16, v129
	v_pk_add_f32 v[124:125], v[120:121], v[120:121] op_sel_hi:[0,1]
	v_cvt_pk_bf16_f32 v120, v154, v155
	v_cvt_pk_bf16_f32 v121, v126, v127
	v_cvt_pk_bf16_f32 v122, v224, v225
	v_cvt_pk_bf16_f32 v123, v222, v223
	global_store_dwordx4 v[220:221], v[120:123], off
	v_lshlrev_b32_e32 v124, 16, v128
	v_and_b32_e32 v172, 0xffff0000, v129
	v_lshl_add_u64 v[120:121], s[54:55], 0, v[228:229]
	v_lshl_add_u64 v[220:221], v[120:121], 0, v[132:133]
	v_sub_f32_e32 v229, v168, v204
	v_sub_f32_e32 v228, v124, v204
	v_sub_f32_e32 v129, v172, v204
	v_sub_f32_e32 v128, v169, v204
	v_pk_mul_f32 v[228:229], v[206:207], v[228:229] op_sel_hi:[0,1]
	v_pk_mul_f32 v[128:129], v[206:207], v[128:129] op_sel_hi:[0,1]
	v_pk_fma_f32 v[228:229], v[72:73], v[228:229], v[76:77]
	v_pk_fma_f32 v[128:129], v[74:75], v[128:129], v[78:79]
	v_cndmask_b32_e64 v229, v229, v168, s[30:31]
	v_cndmask_b32_e64 v228, v228, v124, s[30:31]
	v_lshlrev_b32_e32 v124, 16, v130
	v_and_b32_e32 v168, 0xffff0000, v130
	v_cndmask_b32_e64 v129, v129, v172, s[30:31]
	v_cndmask_b32_e64 v128, v128, v169, s[30:31]
	v_lshlrev_b32_e32 v169, 16, v131
	v_and_b32_e32 v172, 0xffff0000, v131
	v_sub_f32_e32 v131, v168, v204
	v_sub_f32_e32 v130, v124, v204
	v_pk_fma_f32 v[118:119], v[128:129], s[70:71], v[118:119] op_sel_hi:[1,0,1]
	v_sub_f32_e32 v129, v172, v204
	v_sub_f32_e32 v128, v169, v204
	v_pk_mul_f32 v[130:131], v[206:207], v[130:131] op_sel_hi:[0,1]
	v_pk_mul_f32 v[128:129], v[206:207], v[128:129] op_sel_hi:[0,1]
	v_pk_fma_f32 v[130:131], v[64:65], v[130:131], v[68:69]
	v_pk_fma_f32 v[128:129], v[66:67], v[128:129], v[70:71]
	v_cndmask_b32_e64 v131, v131, v168, s[30:31]
	v_cndmask_b32_e64 v130, v130, v124, s[30:31]
	v_pk_fma_f32 v[116:117], v[228:229], s[70:71], v[116:117] op_sel_hi:[1,0,1]
	v_cndmask_b32_e64 v129, v129, v172, s[30:31]
	v_cndmask_b32_e64 v128, v128, v169, s[30:31]
	v_pk_fma_f32 v[130:131], v[130:131], s[70:71], v[112:113] op_sel_hi:[1,0,1]
	v_cvt_pk_bf16_f32 v112, v116, v117
	v_cvt_pk_bf16_f32 v113, v118, v119
	v_pk_fma_f32 v[128:129], v[128:129], s[70:71], v[114:115] op_sel_hi:[1,0,1]
	v_cvt_pk_bf16_f32 v114, v130, v131
	v_mov_b32_e32 v212, v154
	v_cvt_pk_bf16_f32 v115, v128, v129
	global_store_dwordx4 v[226:227], v[112:115], off
	v_mov_b32_e32 v214, v155
	v_mov_b32_e32 v208, v126
	v_lshl_add_u64 v[112:113], s[54:55], 0, v[230:231]
	v_lshl_add_u64 v[226:227], v[112:113], 0, v[132:133]
	v_mov_b32_e32 v210, v127
	v_mov_b32_e32 v204, v224
	v_mov_b32_e32 v206, v225
	v_mul_f32_e32 v199, v154, v154
	v_mul_f32_e32 v201, v155, v155
	v_mul_f32_e32 v157, v126, v126
	v_mul_f32_e32 v159, v127, v127
	s_waitcnt vmcnt(7)
	s_nop 1
	v_mov_b32_e32 v120, v24
	v_mov_b32_e32 v121, v25
	v_mov_b32_e32 v122, v26
	v_mov_b32_e32 v123, v27
	v_lshlrev_b32_e32 v124, 16, v120
	v_and_b32_e32 v168, 0xffff0000, v120
	v_lshlrev_b32_e32 v169, 16, v121
	v_and_b32_e32 v172, 0xffff0000, v121
	v_sub_f32_e32 v121, v172, v202
	v_sub_f32_e32 v120, v169, v202
	v_sub_f32_e32 v229, v168, v202
	v_sub_f32_e32 v228, v124, v202
	v_pk_mul_f32 v[228:229], v[178:179], v[228:229] op_sel_hi:[0,1]
	v_pk_mul_f32 v[120:121], v[178:179], v[120:121] op_sel_hi:[0,1]
	v_pk_fma_f32 v[120:121], v[74:75], v[120:121], v[78:79]
	v_pk_fma_f32 v[228:229], v[72:73], v[228:229], v[76:77]
	v_cndmask_b32_e64 v121, v121, v172, s[30:31]
	v_cndmask_b32_e64 v229, v229, v168, s[30:31]
	v_cndmask_b32_e64 v228, v228, v124, s[30:31]
	v_cndmask_b32_e64 v120, v120, v169, s[30:31]
	v_lshlrev_b32_e32 v124, 16, v122
	v_and_b32_e32 v168, 0xffff0000, v122
	v_lshlrev_b32_e32 v169, 16, v123
	v_and_b32_e32 v172, 0xffff0000, v123
	v_pk_fma_f32 v[110:111], v[120:121], s[70:71], v[110:111] op_sel_hi:[1,0,1]
	v_sub_f32_e32 v121, v172, v202
	v_sub_f32_e32 v120, v169, v202
	v_sub_f32_e32 v123, v168, v202
	v_sub_f32_e32 v122, v124, v202
	v_pk_mul_f32 v[122:123], v[178:179], v[122:123] op_sel_hi:[0,1]
	v_pk_mul_f32 v[120:121], v[178:179], v[120:121] op_sel_hi:[0,1]
	v_pk_fma_f32 v[120:121], v[66:67], v[120:121], v[70:71]
	v_pk_fma_f32 v[122:123], v[64:65], v[122:123], v[68:69]
	v_cndmask_b32_e64 v121, v121, v172, s[30:31]
	v_cndmask_b32_e64 v123, v123, v168, s[30:31]
	v_cndmask_b32_e64 v122, v122, v124, s[30:31]
	v_cndmask_b32_e64 v120, v120, v169, s[30:31]
	v_pk_fma_f32 v[108:109], v[228:229], s[70:71], v[108:109] op_sel_hi:[1,0,1]
	v_pk_fma_f32 v[106:107], v[120:121], s[70:71], v[106:107] op_sel_hi:[1,0,1]
	v_pk_fma_f32 v[104:105], v[122:123], s[70:71], v[104:105] op_sel_hi:[1,0,1]
	v_cvt_pk_bf16_f32 v120, v108, v109
	v_cvt_pk_bf16_f32 v121, v110, v111
	v_mov_b32_e32 v202, v223
	v_cvt_pk_bf16_f32 v122, v104, v105
	v_cvt_pk_bf16_f32 v123, v106, v107
	global_store_dwordx4 v[220:221], v[120:123], off
	s_waitcnt vmcnt(7)
	s_nop 1
	v_mov_b32_e32 v112, v28
	v_mov_b32_e32 v113, v29
	v_mov_b32_e32 v114, v30
	v_mov_b32_e32 v115, v31
	v_lshlrev_b32_e32 v124, 16, v113
	v_and_b32_e32 v168, 0xffff0000, v113
	v_lshlrev_b32_e32 v122, 16, v112
	v_and_b32_e32 v123, 0xffff0000, v112
	v_sub_f32_e32 v113, v168, v196
	v_sub_f32_e32 v112, v124, v196
	v_sub_f32_e32 v121, v123, v196
	v_sub_f32_e32 v120, v122, v196
	v_pk_mul_f32 v[120:121], v[176:177], v[120:121] op_sel_hi:[0,1]
	v_pk_mul_f32 v[112:113], v[176:177], v[112:113] op_sel_hi:[0,1]
	v_pk_fma_f32 v[112:113], v[74:75], v[112:113], v[78:79]
	v_pk_fma_f32 v[120:121], v[72:73], v[120:121], v[76:77]
	v_cndmask_b32_e64 v113, v113, v168, s[30:31]
	v_cndmask_b32_e64 v121, v121, v123, s[30:31]
	v_cndmask_b32_e64 v120, v120, v122, s[30:31]
	v_cndmask_b32_e64 v112, v112, v124, s[30:31]
	v_lshlrev_b32_e32 v122, 16, v115
	v_and_b32_e32 v123, 0xffff0000, v115
	v_pk_fma_f32 v[102:103], v[112:113], s[70:71], v[102:103] op_sel_hi:[1,0,1]
	v_pk_fma_f32 v[100:101], v[120:121], s[70:71], v[100:101] op_sel_hi:[1,0,1]
	v_lshlrev_b32_e32 v120, 16, v114
	v_and_b32_e32 v121, 0xffff0000, v114
	v_sub_f32_e32 v113, v123, v196
	v_sub_f32_e32 v112, v122, v196
	v_sub_f32_e32 v115, v121, v196
	v_sub_f32_e32 v114, v120, v196
	v_pk_mul_f32 v[112:113], v[176:177], v[112:113] op_sel_hi:[0,1]
	v_pk_mul_f32 v[114:115], v[176:177], v[114:115] op_sel_hi:[0,1]
	v_pk_fma_f32 v[112:113], v[66:67], v[112:113], v[70:71]
	v_pk_fma_f32 v[114:115], v[64:65], v[114:115], v[68:69]
	v_cndmask_b32_e64 v113, v113, v123, s[30:31]
	v_cndmask_b32_e64 v112, v112, v122, s[30:31]
	v_cndmask_b32_e64 v115, v115, v121, s[30:31]
	v_cndmask_b32_e64 v114, v114, v120, s[30:31]
	v_pk_fma_f32 v[98:99], v[112:113], s[70:71], v[98:99] op_sel_hi:[1,0,1]
	v_cvt_pk_bf16_f32 v112, v100, v101
	v_cvt_pk_bf16_f32 v113, v102, v103
	v_pk_fma_f32 v[96:97], v[114:115], s[70:71], v[96:97] op_sel_hi:[1,0,1]
	v_mov_b32_e32 v196, v222
	v_cvt_pk_bf16_f32 v114, v96, v97
	v_cvt_pk_bf16_f32 v115, v98, v99
	global_store_dwordx4 v[226:227], v[112:115], off
	v_pk_add_f32 v[120:121], v[196:197], v[202:203]
	v_mov_b32_e32 v124, v175
	v_and_b32_e32 v113, 64, v237
	v_xor_b32_e32 v112, 16, v237
	v_add_u32_e32 v113, 64, v113
	v_cmp_lt_i32_e32 vcc, v112, v113
	v_pk_add_f32 v[114:115], v[208:209], v[210:211]
	s_nop 0
	v_cndmask_b32_e32 v112, v237, v112, vcc
	v_lshlrev_b32_e32 v178, 2, v112
	v_xor_b32_e32 v112, 32, v237
	v_cmp_lt_i32_e32 vcc, v112, v113
	s_nop 1
	v_cndmask_b32_e32 v112, v237, v112, vcc
	v_lshlrev_b32_e32 v176, 2, v112
	v_pk_add_f32 v[112:113], v[212:213], v[214:215]
	s_nop 0
	v_pk_add_f32 v[112:113], v[112:113], v[114:115]
	v_pk_add_f32 v[114:115], v[204:205], v[206:207]
	s_nop 0
	v_pk_add_f32 v[114:115], v[114:115], v[120:121]
	v_pk_add_f32 v[120:121], v[156:157], v[158:159]
	v_pk_add_f32 v[112:113], v[112:113], v[114:115]
	v_pk_add_f32 v[114:115], v[198:199], v[200:201]
	s_nop 0
	v_pk_add_f32 v[114:115], v[114:115], v[120:121]
	s_nop 0
	v_pk_add_f32 v[114:115], v[114:115], v[124:125]
	s_nop 0
	v_pk_add_f32 v[112:113], v[112:113], v[114:115]
	ds_bpermute_b32 v114, v178, v112
	ds_bpermute_b32 v115, v178, v113
	s_waitcnt lgkmcnt(0)
	v_pk_add_f32 v[112:113], v[112:113], v[114:115]
	ds_bpermute_b32 v114, v176, v112
	ds_bpermute_b32 v115, v176, v113
	s_and_saveexec_b64 s[10:11], s[26:27]
	s_cbranch_execz .LBB0_1065
	v_lshlrev_b64 v[120:121], 7, v[188:189]
	v_lshl_add_u64 v[120:121], s[50:51], 0, v[120:121]
	s_waitcnt lgkmcnt(0)
	v_pk_add_f32 v[112:113], v[112:113], v[114:115]
	global_store_dwordx2 v[120:121], v[112:113], off

.LBB0_1079:
	v_add_u32_e32 v102, 0x80, v188
	v_ashrrev_i32_e32 v103, 31, v102
	v_lshlrev_b64 v[126:127], 11, v[102:103]
	v_add_u32_e32 v96, 0x90, v188
	v_lshl_add_u64 v[120:121], s[54:55], 0, v[126:127]
	v_ashrrev_i32_e32 v97, 31, v96
	v_lshl_add_u64 v[122:123], v[192:193], 1, v[120:121]
	v_lshlrev_b64 v[124:125], 11, v[96:97]
	v_lshl_add_u32 v130, v237, 4, s58
	v_add_u32_e32 v131, 0x10000, v130
	ds_read_b128 v[0:3], v130 offset:49152
	ds_read_b128 v[4:7], v130 offset:57344
	ds_read_b128 v[8:11], v131
	ds_read_b128 v[12:15], v131 offset:8192
	ds_read_b128 v[16:19], v130
	ds_read_b128 v[20:23], v130 offset:8192
	ds_read_b128 v[24:27], v131 offset:16384
	ds_read_b128 v[28:31], v131 offset:24576
	s_mov_b32 s101, 0
	s_mov_b32 s100, 0x8000
	v_lshl_add_u64 v[98:99], v[122:123], 0, s[100:101]
	s_mov_b32 s100, 0x10000
	v_lshl_add_u64 v[100:101], v[122:123], 0, s[100:101]
	s_mov_b32 s100, 0x18000
	v_lshl_add_u64 v[128:129], v[122:123], 0, s[100:101]
	global_load_dwordx4 v[192:195], v[122:123], off
	global_load_dwordx4 v[196:199], v[98:99], off
	global_load_dwordx4 v[200:203], v[100:101], off
	global_load_dwordx4 v[204:207], v[128:129], off
	global_load_dwordx4 v[208:211], v[122:123], off offset:256
	global_load_dwordx4 v[212:215], v[98:99], off offset:256
	global_load_dwordx4 v[216:219], v[100:101], off offset:256
	global_load_dwordx4 v[220:223], v[128:129], off offset:256
	s_waitcnt lgkmcnt(0)
	v_lshl_add_u64 v[134:135], v[190:191], 0, v[124:125]
	v_add_u32_e32 v100, 0xa0, v188
	s_waitcnt lgkmcnt(1)
	v_add_u32_e32 v98, 0xb0, v188
	v_ashrrev_i32_e32 v101, 31, v100
	s_waitcnt lgkmcnt(0)
	v_ashrrev_i32_e32 v99, 31, v98
	v_lshlrev_b64 v[130:131], 11, v[100:101]
	v_lshlrev_b64 v[128:129], 11, v[98:99]
	v_lshl_add_u64 v[146:147], v[190:191], 0, v[126:127]
	v_lshl_add_u64 v[136:137], v[190:191], 0, v[130:131]
	v_lshl_add_u64 v[126:127], v[190:191], 0, v[128:129]
	v_lshl_add_u64 v[120:121], v[120:121], 0, v[132:133]
	s_waitcnt vmcnt(7)
	s_nop 1
	v_mov_b32_e32 v138, v192
	v_mov_b32_e32 v139, v193
	v_mov_b32_e32 v140, v194
	v_mov_b32_e32 v141, v195
	v_lshlrev_b32_e32 v105, 16, v138
	v_and_b32_e32 v107, 0xffff0000, v138
	v_lshlrev_b32_e32 v109, 16, v139
	v_and_b32_e32 v111, 0xffff0000, v139
	v_lshlrev_b32_e32 v113, 16, v140
	v_and_b32_e32 v115, 0xffff0000, v140
	v_lshlrev_b32_e32 v117, 16, v141
	v_and_b32_e32 v119, 0xffff0000, v141
	s_waitcnt vmcnt(6)
	s_nop 1
	v_mov_b32_e32 v142, v196
	v_mov_b32_e32 v143, v197
	v_mov_b32_e32 v144, v198
	v_mov_b32_e32 v145, v199
	v_lshlrev_b32_e32 v156, 16, v142
	v_and_b32_e32 v157, 0xffff0000, v142
	v_lshlrev_b32_e32 v158, 16, v143
	v_and_b32_e32 v159, 0xffff0000, v143
	v_lshlrev_b32_e32 v160, 16, v144
	v_and_b32_e32 v161, 0xffff0000, v144
	v_lshlrev_b32_e32 v162, 16, v145
	v_and_b32_e32 v163, 0xffff0000, v145
	v_sub_f32_e32 v139, v111, v118
	v_sub_f32_e32 v138, v109, v118
	v_sub_f32_e32 v141, v107, v118
	v_sub_f32_e32 v140, v105, v118
	v_sub_f32_e32 v143, v119, v118
	v_sub_f32_e32 v142, v117, v118
	v_sub_f32_e32 v145, v115, v118
	v_sub_f32_e32 v144, v113, v118
	v_sub_f32_e32 v149, v159, v114
	v_sub_f32_e32 v148, v158, v114
	v_sub_f32_e32 v151, v157, v114
	v_sub_f32_e32 v150, v156, v114
	v_sub_f32_e32 v153, v163, v114
	v_sub_f32_e32 v152, v162, v114
	v_sub_f32_e32 v155, v161, v114
	v_sub_f32_e32 v154, v160, v114
	v_pk_mul_f32 v[140:141], v[116:117], v[140:141] op_sel_hi:[0,1]
	v_pk_mul_f32 v[138:139], v[116:117], v[138:139] op_sel_hi:[0,1]
	v_pk_mul_f32 v[144:145], v[116:117], v[144:145] op_sel_hi:[0,1]
	v_pk_mul_f32 v[142:143], v[116:117], v[142:143] op_sel_hi:[0,1]
	v_pk_mul_f32 v[150:151], v[112:113], v[150:151] op_sel_hi:[0,1]
	v_pk_mul_f32 v[148:149], v[112:113], v[148:149] op_sel_hi:[0,1]
	v_pk_mul_f32 v[154:155], v[112:113], v[154:155] op_sel_hi:[0,1]
	v_pk_mul_f32 v[152:153], v[112:113], v[152:153] op_sel_hi:[0,1]
	v_pk_fma_f32 v[138:139], v[90:91], v[138:139], v[94:95]
	v_pk_fma_f32 v[140:141], v[88:89], v[140:141], v[92:93]
	v_pk_fma_f32 v[142:143], v[82:83], v[142:143], v[86:87]
	v_pk_fma_f32 v[144:145], v[80:81], v[144:145], v[84:85]
	v_pk_fma_f32 v[148:149], v[90:91], v[148:149], v[94:95]
	v_pk_fma_f32 v[150:151], v[88:89], v[150:151], v[92:93]
	v_pk_fma_f32 v[152:153], v[82:83], v[152:153], v[86:87]
	v_pk_fma_f32 v[154:155], v[80:81], v[154:155], v[84:85]
	v_cndmask_b32_e64 v141, v141, v107, s[30:31]
	v_cndmask_b32_e64 v140, v140, v105, s[30:31]
	v_cndmask_b32_e64 v139, v139, v111, s[30:31]
	v_cndmask_b32_e64 v138, v138, v109, s[30:31]
	v_cndmask_b32_e64 v145, v145, v115, s[30:31]
	v_cndmask_b32_e64 v144, v144, v113, s[30:31]
	v_cndmask_b32_e64 v143, v143, v119, s[30:31]
	v_cndmask_b32_e64 v142, v142, v117, s[30:31]
	v_cndmask_b32_e64 v151, v151, v157, s[30:31]
	v_cndmask_b32_e64 v150, v150, v156, s[30:31]
	v_pk_fma_f32 v[62:63], v[138:139], s[70:71], v[62:63] op_sel_hi:[1,0,1]
	v_pk_fma_f32 v[60:61], v[140:141], s[70:71], v[60:61] op_sel_hi:[1,0,1]
	v_pk_fma_f32 v[58:59], v[142:143], s[70:71], v[58:59] op_sel_hi:[1,0,1]
	v_pk_fma_f32 v[56:57], v[144:145], s[70:71], v[56:57] op_sel_hi:[1,0,1]
	v_cvt_pk_bf16_f32 v138, v60, v61
	v_cvt_pk_bf16_f32 v139, v62, v63
	v_cndmask_b32_e64 v149, v149, v159, s[30:31]
	v_cvt_pk_bf16_f32 v140, v56, v57
	v_cvt_pk_bf16_f32 v141, v58, v59
	v_cndmask_b32_e64 v148, v148, v158, s[30:31]
	v_cndmask_b32_e64 v155, v155, v161, s[30:31]
	v_cndmask_b32_e64 v154, v154, v160, s[30:31]
	v_cndmask_b32_e64 v153, v153, v163, s[30:31]
	v_cndmask_b32_e64 v152, v152, v162, s[30:31]
	v_pk_fma_f32 v[54:55], v[148:149], s[70:71], v[54:55] op_sel_hi:[1,0,1]
	v_pk_fma_f32 v[52:53], v[150:151], s[70:71], v[52:53] op_sel_hi:[1,0,1]
	v_pk_fma_f32 v[50:51], v[152:153], s[70:71], v[50:51] op_sel_hi:[1,0,1]
	v_pk_fma_f32 v[48:49], v[154:155], s[70:71], v[48:49] op_sel_hi:[1,0,1]
	global_store_dwordx4 v[146:147], v[138:141], off
	s_waitcnt vmcnt(6)
	s_nop 1
	v_mov_b32_e32 v142, v200
	v_mov_b32_e32 v143, v201
	v_mov_b32_e32 v144, v202
	v_mov_b32_e32 v145, v203
	v_lshlrev_b32_e32 v105, 16, v142
	v_cvt_pk_bf16_f32 v138, v52, v53
	v_cvt_pk_bf16_f32 v139, v54, v55
	v_cvt_pk_bf16_f32 v140, v48, v49
	v_cvt_pk_bf16_f32 v141, v50, v51
	v_and_b32_e32 v107, 0xffff0000, v142
	v_lshlrev_b32_e32 v109, 16, v143
	v_and_b32_e32 v111, 0xffff0000, v143
	v_lshlrev_b32_e32 v113, 16, v144
	v_and_b32_e32 v115, 0xffff0000, v144
	v_lshlrev_b32_e32 v117, 16, v145
	v_and_b32_e32 v119, 0xffff0000, v145
	global_store_dwordx4 v[134:135], v[138:141], off
	v_sub_f32_e32 v135, v111, v110
	v_sub_f32_e32 v134, v109, v110
	v_sub_f32_e32 v139, v107, v110
	v_sub_f32_e32 v138, v105, v110
	v_sub_f32_e32 v141, v119, v110
	v_sub_f32_e32 v140, v117, v110
	v_sub_f32_e32 v143, v115, v110
	v_sub_f32_e32 v142, v113, v110
	v_pk_mul_f32 v[138:139], v[108:109], v[138:139] op_sel_hi:[0,1]
	v_pk_mul_f32 v[134:135], v[108:109], v[134:135] op_sel_hi:[0,1]
	v_pk_mul_f32 v[142:143], v[108:109], v[142:143] op_sel_hi:[0,1]
	v_pk_mul_f32 v[140:141], v[108:109], v[140:141] op_sel_hi:[0,1]
	v_pk_fma_f32 v[134:135], v[90:91], v[134:135], v[94:95]
	v_pk_fma_f32 v[138:139], v[88:89], v[138:139], v[92:93]
	v_pk_fma_f32 v[140:141], v[82:83], v[140:141], v[86:87]
	v_pk_fma_f32 v[142:143], v[80:81], v[142:143], v[84:85]
	v_cndmask_b32_e64 v139, v139, v107, s[30:31]
	v_cndmask_b32_e64 v138, v138, v105, s[30:31]
	v_cndmask_b32_e64 v135, v135, v111, s[30:31]
	v_cndmask_b32_e64 v134, v134, v109, s[30:31]
	v_cndmask_b32_e64 v143, v143, v115, s[30:31]
	v_cndmask_b32_e64 v142, v142, v113, s[30:31]
	v_cndmask_b32_e64 v141, v141, v119, s[30:31]
	v_cndmask_b32_e64 v140, v140, v117, s[30:31]
	v_pk_fma_f32 v[46:47], v[134:135], s[70:71], v[46:47] op_sel_hi:[1,0,1]
	v_pk_fma_f32 v[44:45], v[138:139], s[70:71], v[44:45] op_sel_hi:[1,0,1]
	v_pk_fma_f32 v[42:43], v[140:141], s[70:71], v[42:43] op_sel_hi:[1,0,1]
	v_pk_fma_f32 v[40:41], v[142:143], s[70:71], v[40:41] op_sel_hi:[1,0,1]
	s_waitcnt vmcnt(6)
	s_nop 1
	v_mov_b32_e32 v146, v204
	v_mov_b32_e32 v147, v205
	v_mov_b32_e32 v148, v206
	v_mov_b32_e32 v149, v207
	v_lshlrev_b32_e32 v152, 16, v146
	v_and_b32_e32 v153, 0xffff0000, v146
	v_lshlrev_b32_e32 v154, 16, v147
	v_and_b32_e32 v155, 0xffff0000, v147
	v_lshlrev_b32_e32 v156, 16, v148
	v_and_b32_e32 v157, 0xffff0000, v148
	v_lshlrev_b32_e32 v158, 16, v149
	v_and_b32_e32 v159, 0xffff0000, v149
	v_sub_f32_e32 v145, v155, v106
	v_sub_f32_e32 v144, v154, v106
	v_sub_f32_e32 v147, v153, v106
	v_sub_f32_e32 v146, v152, v106
	v_sub_f32_e32 v149, v159, v106
	v_sub_f32_e32 v148, v158, v106
	v_sub_f32_e32 v151, v157, v106
	v_sub_f32_e32 v150, v156, v106
	v_pk_mul_f32 v[146:147], v[104:105], v[146:147] op_sel_hi:[0,1]
	v_pk_mul_f32 v[144:145], v[104:105], v[144:145] op_sel_hi:[0,1]
	v_pk_mul_f32 v[150:151], v[104:105], v[150:151] op_sel_hi:[0,1]
	v_pk_mul_f32 v[148:149], v[104:105], v[148:149] op_sel_hi:[0,1]
	v_pk_fma_f32 v[90:91], v[90:91], v[144:145], v[94:95]
	v_pk_fma_f32 v[88:89], v[88:89], v[146:147], v[92:93]
	v_pk_fma_f32 v[82:83], v[82:83], v[148:149], v[86:87]
	v_pk_fma_f32 v[80:81], v[80:81], v[150:151], v[84:85]
	v_cndmask_b32_e64 v85, v89, v153, s[30:31]
	v_cndmask_b32_e64 v84, v88, v152, s[30:31]
	v_cndmask_b32_e64 v87, v91, v155, s[30:31]
	v_cndmask_b32_e64 v86, v90, v154, s[30:31]
	v_cndmask_b32_e64 v89, v81, v157, s[30:31]
	v_cndmask_b32_e64 v88, v80, v156, s[30:31]
	v_cndmask_b32_e64 v91, v83, v159, s[30:31]
	v_cndmask_b32_e64 v90, v82, v158, s[30:31]
	v_cvt_pk_bf16_f32 v80, v44, v45
	v_cvt_pk_bf16_f32 v81, v46, v47
	v_cvt_pk_bf16_f32 v82, v40, v41
	v_cvt_pk_bf16_f32 v83, v42, v43
	v_pk_fma_f32 v[38:39], v[86:87], s[70:71], v[38:39] op_sel_hi:[1,0,1]
	v_pk_fma_f32 v[36:37], v[84:85], s[70:71], v[36:37] op_sel_hi:[1,0,1]
	global_store_dwordx4 v[136:137], v[80:83], off
	v_pk_fma_f32 v[34:35], v[90:91], s[70:71], v[34:35] op_sel_hi:[1,0,1]
	v_pk_fma_f32 v[32:33], v[88:89], s[70:71], v[32:33] op_sel_hi:[1,0,1]
	v_cvt_pk_bf16_f32 v84, v36, v37
	v_cvt_pk_bf16_f32 v85, v38, v39
	v_lshl_add_u64 v[80:81], s[54:55], 0, v[124:125]
	v_cvt_pk_bf16_f32 v86, v32, v33
	v_cvt_pk_bf16_f32 v87, v34, v35
	v_lshl_add_u64 v[82:83], v[80:81], 0, v[132:133]
	v_lshl_add_u64 v[80:81], s[54:55], 0, v[130:131]
	v_lshl_add_u64 v[122:123], s[54:55], 0, v[128:129]
	v_lshl_add_u64 v[124:125], v[80:81], 0, v[132:133]
	v_lshl_add_u64 v[80:81], v[122:123], 0, v[132:133]
	global_store_dwordx4 v[126:127], v[84:87], off
	s_waitcnt vmcnt(7)
	s_nop 1
	v_mov_b32_e32 v88, v208
	v_mov_b32_e32 v89, v209
	v_mov_b32_e32 v90, v210
	v_mov_b32_e32 v91, v211
	v_lshlrev_b32_e32 v105, 16, v88
	v_and_b32_e32 v107, 0xffff0000, v88
	v_lshlrev_b32_e32 v109, 16, v89
	v_and_b32_e32 v111, 0xffff0000, v89
	v_lshlrev_b32_e32 v117, 16, v90
	v_and_b32_e32 v122, 0xffff0000, v90
	v_lshlrev_b32_e32 v123, 16, v91
	v_and_b32_e32 v126, 0xffff0000, v91
	v_sub_f32_e32 v85, v111, v118
	v_sub_f32_e32 v84, v109, v118
	v_sub_f32_e32 v87, v107, v118
	v_sub_f32_e32 v86, v105, v118
	v_sub_f32_e32 v89, v126, v118
	v_sub_f32_e32 v88, v123, v118
	v_sub_f32_e32 v91, v122, v118
	v_sub_f32_e32 v90, v117, v118
	v_pk_mul_f32 v[86:87], v[116:117], v[86:87] op_sel_hi:[0,1]
	v_pk_mul_f32 v[84:85], v[116:117], v[84:85] op_sel_hi:[0,1]
	v_pk_mul_f32 v[90:91], v[116:117], v[90:91] op_sel_hi:[0,1]
	v_pk_mul_f32 v[88:89], v[116:117], v[88:89] op_sel_hi:[0,1]
	s_waitcnt vmcnt(6)
	s_nop 1
	v_mov_b32_e32 v92, v212
	v_mov_b32_e32 v93, v213
	v_mov_b32_e32 v94, v214
	v_mov_b32_e32 v95, v215
	v_lshlrev_b32_e32 v127, 16, v92
	v_and_b32_e32 v128, 0xffff0000, v92
	v_lshlrev_b32_e32 v129, 16, v93
	v_and_b32_e32 v130, 0xffff0000, v93
	v_lshlrev_b32_e32 v131, 16, v94
	v_and_b32_e32 v132, 0xffff0000, v94
	v_lshlrev_b32_e32 v133, 16, v95
	v_and_b32_e32 v134, 0xffff0000, v95
	v_pk_fma_f32 v[84:85], v[74:75], v[84:85], v[78:79]
	v_pk_fma_f32 v[86:87], v[72:73], v[86:87], v[76:77]
	v_pk_fma_f32 v[88:89], v[66:67], v[88:89], v[70:71]
	v_pk_fma_f32 v[90:91], v[64:65], v[90:91], v[68:69]
	v_sub_f32_e32 v93, v130, v114
	v_sub_f32_e32 v92, v129, v114
	v_sub_f32_e32 v95, v128, v114
	v_sub_f32_e32 v94, v127, v114
	v_sub_f32_e32 v119, v134, v114
	v_sub_f32_e32 v118, v133, v114
	v_sub_f32_e32 v115, v132, v114
	v_sub_f32_e32 v114, v131, v114
	v_cndmask_b32_e64 v87, v87, v107, s[30:31]
	v_cndmask_b32_e64 v86, v86, v105, s[30:31]
	v_cndmask_b32_e64 v85, v85, v111, s[30:31]
	v_cndmask_b32_e64 v84, v84, v109, s[30:31]
	v_cndmask_b32_e64 v91, v91, v122, s[30:31]
	v_cndmask_b32_e64 v90, v90, v117, s[30:31]
	v_cndmask_b32_e64 v89, v89, v126, s[30:31]
	v_cndmask_b32_e64 v88, v88, v123, s[30:31]
	v_pk_mul_f32 v[94:95], v[112:113], v[94:95] op_sel_hi:[0,1]
	v_pk_mul_f32 v[92:93], v[112:113], v[92:93] op_sel_hi:[0,1]
	v_pk_mul_f32 v[114:115], v[112:113], v[114:115] op_sel_hi:[0,1]
	v_pk_mul_f32 v[112:113], v[112:113], v[118:119] op_sel_hi:[0,1]
	v_pk_fma_f32 v[116:117], v[84:85], s[70:71], v[30:31] op_sel_hi:[1,0,1]
	v_pk_fma_f32 v[118:119], v[86:87], s[70:71], v[28:29] op_sel_hi:[1,0,1]
	v_pk_fma_f32 v[88:89], v[88:89], s[70:71], v[26:27] op_sel_hi:[1,0,1]
	v_pk_fma_f32 v[90:91], v[90:91], s[70:71], v[24:25] op_sel_hi:[1,0,1]
	v_cvt_pk_bf16_f32 v24, v118, v119
	v_cvt_pk_bf16_f32 v25, v116, v117
	v_pk_fma_f32 v[92:93], v[74:75], v[92:93], v[78:79]
	v_cvt_pk_bf16_f32 v26, v90, v91
	v_cvt_pk_bf16_f32 v27, v88, v89
	v_pk_fma_f32 v[94:95], v[72:73], v[94:95], v[76:77]
	v_pk_fma_f32 v[112:113], v[66:67], v[112:113], v[70:71]
	v_pk_fma_f32 v[114:115], v[64:65], v[114:115], v[68:69]
	v_cndmask_b32_e64 v95, v95, v128, s[30:31]
	v_cndmask_b32_e64 v94, v94, v127, s[30:31]
	v_cndmask_b32_e64 v85, v93, v130, s[30:31]
	v_cndmask_b32_e64 v84, v92, v129, s[30:31]
	v_cndmask_b32_e64 v87, v115, v132, s[30:31]
	v_cndmask_b32_e64 v86, v114, v131, s[30:31]
	v_cndmask_b32_e64 v93, v113, v134, s[30:31]
	v_cndmask_b32_e64 v92, v112, v133, s[30:31]
	v_pk_fma_f32 v[22:23], v[84:85], s[70:71], v[22:23] op_sel_hi:[1,0,1]
	v_pk_fma_f32 v[20:21], v[94:95], s[70:71], v[20:21] op_sel_hi:[1,0,1]
	v_pk_fma_f32 v[18:19], v[92:93], s[70:71], v[18:19] op_sel_hi:[1,0,1]
	v_pk_fma_f32 v[16:17], v[86:87], s[70:71], v[16:17] op_sel_hi:[1,0,1]
	global_store_dwordx4 v[120:121], v[24:27], off
	v_pk_mul_f32 v[120:121], v[88:89], v[88:89]
	v_pk_mul_f32 v[122:123], v[90:91], v[90:91]
	v_cvt_pk_bf16_f32 v24, v20, v21
	v_cvt_pk_bf16_f32 v25, v22, v23
	v_cvt_pk_bf16_f32 v26, v16, v17
	v_cvt_pk_bf16_f32 v27, v18, v19
	v_pk_mov_b32 v[126:127], v[122:123], v[120:121] op_sel:[1,0]
	v_mov_b32_e32 v123, v121
	v_pk_add_f32 v[120:121], v[126:127], v[122:123]
	global_store_dwordx4 v[82:83], v[24:27], off
	v_pk_add_f32 v[82:83], v[120:121], v[120:121] op_sel_hi:[0,1]
	v_add_f32_e32 v92, v60, v61
	v_add_f32_e32 v94, v62, v63
	v_add_f32_e32 v112, v56, v57
	v_add_f32_e32 v114, v58, v59
	v_mul_f32_e32 v105, v60, v60
	v_mul_f32_e32 v107, v62, v62
	v_mul_f32_e32 v109, v56, v56
	v_mul_f32_e32 v111, v58, v58
	v_mul_f32_e32 v61, v61, v61
	v_mul_f32_e32 v63, v63, v63
	v_mul_f32_e32 v57, v57, v57
	v_mul_f32_e32 v59, v59, v59
	v_mul_f32_e32 v93, v118, v118
	v_mul_f32_e32 v95, v119, v119
	v_mul_f32_e32 v113, v116, v116
	v_mul_f32_e32 v115, v117, v117
	s_waitcnt vmcnt(7)
	s_nop 1
	v_mov_b32_e32 v28, v216
	v_mov_b32_e32 v29, v217
	v_mov_b32_e32 v30, v218
	v_mov_b32_e32 v31, v219
	v_lshlrev_b32_e32 v56, 16, v28
	v_and_b32_e32 v58, 0xffff0000, v28
	v_lshlrev_b32_e32 v60, 16, v29
	v_and_b32_e32 v62, 0xffff0000, v29
	v_lshlrev_b32_e32 v82, 16, v30
	v_and_b32_e32 v122, 0xffff0000, v30
	v_lshlrev_b32_e32 v123, 16, v31
	v_and_b32_e32 v126, 0xffff0000, v31
	v_sub_f32_e32 v25, v62, v110
	v_sub_f32_e32 v24, v60, v110
	v_sub_f32_e32 v27, v58, v110
	v_sub_f32_e32 v26, v56, v110
	v_sub_f32_e32 v29, v126, v110
	v_sub_f32_e32 v28, v123, v110
	v_sub_f32_e32 v31, v122, v110
	v_sub_f32_e32 v30, v82, v110
	v_pk_mul_f32 v[26:27], v[108:109], v[26:27] op_sel_hi:[0,1]
	v_pk_mul_f32 v[24:25], v[108:109], v[24:25] op_sel_hi:[0,1]
	v_pk_mul_f32 v[30:31], v[108:109], v[30:31] op_sel_hi:[0,1]
	v_pk_mul_f32 v[28:29], v[108:109], v[28:29] op_sel_hi:[0,1]
	v_pk_fma_f32 v[24:25], v[74:75], v[24:25], v[78:79]
	v_pk_fma_f32 v[26:27], v[72:73], v[26:27], v[76:77]
	v_pk_fma_f32 v[28:29], v[66:67], v[28:29], v[70:71]
	s_waitcnt vmcnt(6)
	s_nop 1
	v_mov_b32_e32 v84, v220
	v_mov_b32_e32 v85, v221
	v_mov_b32_e32 v86, v222
	v_mov_b32_e32 v87, v223
	v_lshlrev_b32_e32 v110, 16, v84
	v_and_b32_e32 v127, 0xffff0000, v84
	v_lshlrev_b32_e32 v128, 16, v85
	v_and_b32_e32 v129, 0xffff0000, v85
	v_pk_fma_f32 v[30:31], v[64:65], v[30:31], v[68:69]
	v_sub_f32_e32 v85, v129, v106
	v_sub_f32_e32 v84, v128, v106
	v_sub_f32_e32 v121, v127, v106
	v_sub_f32_e32 v120, v110, v106
	v_cndmask_b32_e64 v27, v27, v58, s[30:31]
	v_cndmask_b32_e64 v26, v26, v56, s[30:31]
	v_cndmask_b32_e64 v25, v25, v62, s[30:31]
	v_cndmask_b32_e64 v24, v24, v60, s[30:31]
	v_cndmask_b32_e64 v31, v31, v122, s[30:31]
	v_cndmask_b32_e64 v30, v30, v82, s[30:31]
	v_cndmask_b32_e64 v29, v29, v126, s[30:31]
	v_cndmask_b32_e64 v28, v28, v123, s[30:31]
	v_pk_mul_f32 v[120:121], v[104:105], v[120:121] op_sel_hi:[0,1]
	v_pk_mul_f32 v[84:85], v[104:105], v[84:85] op_sel_hi:[0,1]
	v_pk_fma_f32 v[14:15], v[24:25], s[70:71], v[14:15] op_sel_hi:[1,0,1]
	v_pk_fma_f32 v[12:13], v[26:27], s[70:71], v[12:13] op_sel_hi:[1,0,1]
	v_pk_fma_f32 v[10:11], v[28:29], s[70:71], v[10:11] op_sel_hi:[1,0,1]
	v_pk_fma_f32 v[8:9], v[30:31], s[70:71], v[8:9] op_sel_hi:[1,0,1]
	v_cvt_pk_bf16_f32 v24, v12, v13
	v_cvt_pk_bf16_f32 v25, v14, v15
	v_lshlrev_b32_e32 v28, 16, v86
	v_cvt_pk_bf16_f32 v26, v8, v9
	v_cvt_pk_bf16_f32 v27, v10, v11
	global_store_dwordx4 v[124:125], v[24:27], off
	v_and_b32_e32 v29, 0xffff0000, v86
	v_and_b32_e32 v30, 0xffff0000, v87
	v_pk_fma_f32 v[24:25], v[74:75], v[84:85], v[78:79]
	v_pk_fma_f32 v[26:27], v[72:73], v[120:121], v[76:77]
	v_cndmask_b32_e64 v25, v25, v129, s[30:31]
	v_cndmask_b32_e64 v27, v27, v127, s[30:31]
	v_cndmask_b32_e64 v26, v26, v110, s[30:31]
	v_cndmask_b32_e64 v24, v24, v128, s[30:31]
	v_lshlrev_b32_e32 v72, 16, v87
	v_pk_fma_f32 v[6:7], v[24:25], s[70:71], v[6:7] op_sel_hi:[1,0,1]
	v_pk_fma_f32 v[4:5], v[26:27], s[70:71], v[4:5] op_sel_hi:[1,0,1]
	v_sub_f32_e32 v25, v30, v106
	v_sub_f32_e32 v24, v72, v106
	v_sub_f32_e32 v27, v29, v106
	v_sub_f32_e32 v26, v28, v106
	v_pk_mul_f32 v[26:27], v[104:105], v[26:27] op_sel_hi:[0,1]
	v_pk_mul_f32 v[24:25], v[104:105], v[24:25] op_sel_hi:[0,1]
	v_pk_fma_f32 v[24:25], v[66:67], v[24:25], v[70:71]
	v_pk_fma_f32 v[26:27], v[64:65], v[26:27], v[68:69]
	v_mov_b32_e32 v104, v118
	v_mov_b32_e32 v60, v119
	v_mov_b32_e32 v106, v116
	v_mov_b32_e32 v62, v117
	v_cndmask_b32_e64 v27, v27, v29, s[30:31]
	v_cndmask_b32_e64 v26, v26, v28, s[30:31]
	v_cndmask_b32_e64 v25, v25, v30, s[30:31]
	v_pk_add_f32 v[28:29], v[104:105], v[60:61]
	v_pk_add_f32 v[30:31], v[106:107], v[62:63]
	v_mov_b32_e32 v108, v90
	v_mov_b32_e32 v56, v91
	v_mov_b32_e32 v110, v88
	v_mov_b32_e32 v58, v89
	v_pk_add_f32 v[28:29], v[28:29], v[30:31]
	v_pk_add_f32 v[30:31], v[108:109], v[56:57]
	v_pk_add_f32 v[56:57], v[110:111], v[58:59]
	v_mov_b32_e32 v82, v175
	v_pk_add_f32 v[30:31], v[30:31], v[56:57]
	v_pk_add_f32 v[56:57], v[112:113], v[114:115]
	v_pk_add_f32 v[28:29], v[28:29], v[30:31]
	v_pk_add_f32 v[30:31], v[92:93], v[94:95]
	v_cndmask_b32_e64 v24, v24, v72, s[30:31]
	v_pk_add_f32 v[30:31], v[30:31], v[56:57]
	v_pk_fma_f32 v[2:3], v[24:25], s[70:71], v[2:3] op_sel_hi:[1,0,1]
	v_pk_add_f32 v[30:31], v[30:31], v[82:83]
	v_pk_fma_f32 v[0:1], v[26:27], s[70:71], v[0:1] op_sel_hi:[1,0,1]
	v_pk_add_f32 v[30:31], v[28:29], v[30:31]
	ds_bpermute_b32 v56, v178, v30
	ds_bpermute_b32 v57, v178, v31
	v_cvt_pk_bf16_f32 v28, v4, v5
	v_cvt_pk_bf16_f32 v29, v6, v7
	s_waitcnt lgkmcnt(0)
	v_pk_add_f32 v[24:25], v[30:31], v[56:57]
	ds_bpermute_b32 v26, v176, v24
	ds_bpermute_b32 v27, v176, v25
	v_cvt_pk_bf16_f32 v30, v0, v1
	v_cvt_pk_bf16_f32 v31, v2, v3
	global_store_dwordx4 v[80:81], v[28:31], off
	s_and_saveexec_b64 s[10:11], s[26:27]
	s_cbranch_execz .LBB0_1081
	v_lshlrev_b64 v[28:29], 7, v[102:103]
	v_lshl_add_u64 v[28:29], s[50:51], 0, v[28:29]
	s_waitcnt lgkmcnt(0)
	v_pk_add_f32 v[24:25], v[24:25], v[26:27]
	global_store_dwordx2 v[28:29], v[24:25], off

.LBB0_1351:
	s_add_u32 s10, s42, 0xfff00080
	s_addc_u32 s11, s43, -1
	s_add_i32 s45, 0, 0x10000
	v_add_u32_e32 v76, s45, v222
	ds_read_b128 v[64:67], v76
	ds_read_b128 v[68:71], v76 offset:1024
	ds_read_b128 v[72:75], v76 offset:2048
	ds_read_b128 v[76:79], v76 offset:3072
	s_cmp_eq_u32 s44, 60
	s_cselect_b32 s13, s16, s11
	s_cselect_b32 s12, s17, s10
	s_cselect_b32 s11, s20, s37
	s_cselect_b32 s10, s21, s35
	v_lshl_add_u64 v[168:169], s[42:43], 0, v[188:189]
	s_add_i32 m0, s54, 0xc000
	ds_read_b128 v[96:99], v227
	ds_read_b128 v[100:103], v227 offset:1024
	ds_read_b128 v[104:107], v227 offset:2048
	ds_read_b128 v[108:111], v227 offset:3072
	ds_read_b128 v[160:163], v227 offset:4096
	ds_read_b128 v[164:167], v227 offset:5120
	ds_read_b128 v[192:195], v227 offset:6144
	ds_read_b128 v[196:199], v227 offset:7168
	global_load_lds_dwordx4 v[168:169], off
	v_lshl_add_u64 v[168:169], s[42:43], 0, v[190:191]
	s_add_i32 m0, s54, 0xe000
	s_nop 0
	global_load_lds_dwordx4 v[168:169], off
	s_waitcnt lgkmcnt(8)
	s_barrier
	s_waitcnt lgkmcnt(0)
	s_setprio 1
	s_waitcnt lgkmcnt(0)
	v_mfma_f32_16x16x32_bf16 v[156:159], v[64:67], v[96:99], v[156:159]
	v_mfma_f32_16x16x32_bf16 v[152:155], v[72:75], v[96:99], v[152:155]
	v_mfma_f32_16x16x32_bf16 v[148:151], v[64:67], v[104:107], v[148:151]
	v_mfma_f32_16x16x32_bf16 v[144:147], v[72:75], v[104:107], v[144:147]
	v_mfma_f32_16x16x32_bf16 v[140:143], v[64:67], v[160:163], v[140:143]
	v_mfma_f32_16x16x32_bf16 v[136:139], v[72:75], v[160:163], v[136:139]
	v_mfma_f32_16x16x32_bf16 v[132:135], v[64:67], v[192:195], v[132:135]
	v_mfma_f32_16x16x32_bf16 v[128:131], v[72:75], v[192:195], v[128:131]
	v_mfma_f32_16x16x32_bf16 v[156:159], v[68:71], v[100:103], v[156:159]
	v_mfma_f32_16x16x32_bf16 v[152:155], v[76:79], v[100:103], v[152:155]
	v_mfma_f32_16x16x32_bf16 v[148:151], v[68:71], v[108:111], v[148:151]
	v_mfma_f32_16x16x32_bf16 v[144:147], v[76:79], v[108:111], v[144:147]
	v_mfma_f32_16x16x32_bf16 v[140:143], v[68:71], v[164:167], v[140:143]
	v_mfma_f32_16x16x32_bf16 v[136:139], v[76:79], v[164:167], v[136:139]
	v_mfma_f32_16x16x32_bf16 v[132:135], v[68:71], v[196:199], v[132:135]
	v_mfma_f32_16x16x32_bf16 v[128:131], v[76:79], v[196:199], v[128:131]
	s_setprio 0
	s_barrier
	s_add_i32 s78, 0, 0x14000
	v_add_u32_e32 v168, s78, v222
	s_add_i32 s45, s45, s47
	ds_read_b128 v[200:203], v168
	ds_read_b128 v[204:207], v168 offset:1024
	ds_read_b128 v[208:211], v168 offset:2048
	ds_read_b128 v[212:215], v168 offset:3072
	v_lshl_add_u64 v[168:169], s[10:11], 0, v[174:175]
	s_mov_b32 m0, s45
	v_lshl_add_u64 v[172:173], s[10:11], 0, v[182:183]
	global_load_lds_dwordx4 v[168:169], off
	s_add_i32 m0, s45, 0x2000
	s_nop 0
	global_load_lds_dwordx4 v[172:173], off
	s_barrier
	s_waitcnt lgkmcnt(0)
	s_setprio 1
	s_waitcnt lgkmcnt(0)
	v_mfma_f32_16x16x32_bf16 v[124:127], v[200:203], v[96:99], v[124:127]
	v_mfma_f32_16x16x32_bf16 v[96:99], v[208:211], v[96:99], v[120:123]
	v_mfma_f32_16x16x32_bf16 v[92:95], v[200:203], v[160:163], v[92:95]
	v_mfma_f32_16x16x32_bf16 v[88:91], v[208:211], v[160:163], v[88:91]
	v_mfma_f32_16x16x32_bf16 v[84:87], v[200:203], v[192:195], v[84:87]
	v_mfma_f32_16x16x32_bf16 v[80:83], v[208:211], v[192:195], v[80:83]
	v_mfma_f32_16x16x32_bf16 v[124:127], v[204:207], v[100:103], v[124:127]
	v_mfma_f32_16x16x32_bf16 v[96:99], v[212:215], v[100:103], v[96:99]
	v_mfma_f32_16x16x32_bf16 v[100:103], v[200:203], v[104:107], v[116:119]
	v_mfma_f32_16x16x32_bf16 v[104:107], v[208:211], v[104:107], v[112:115]
	v_mfma_f32_16x16x32_bf16 v[92:95], v[204:207], v[164:167], v[92:95]
	v_mfma_f32_16x16x32_bf16 v[88:91], v[212:215], v[164:167], v[88:91]
	v_mfma_f32_16x16x32_bf16 v[84:87], v[204:207], v[196:199], v[84:87]
	v_mfma_f32_16x16x32_bf16 v[80:83], v[212:215], v[196:199], v[80:83]
	v_mfma_f32_16x16x32_bf16 v[100:103], v[204:207], v[108:111], v[100:103]
	v_mfma_f32_16x16x32_bf16 v[104:107], v[212:215], v[108:111], v[104:107]
	s_setprio 0
	s_mov_b32 m0, s54
	v_lshl_add_u64 v[216:217], s[12:13], 0, v[186:187]
	s_barrier
	ds_read_b128 v[108:111], v227 offset:16384
	ds_read_b128 v[112:115], v227 offset:17408
	ds_read_b128 v[116:119], v227 offset:18432
	ds_read_b128 v[120:123], v227 offset:19456
	ds_read_b128 v[160:163], v227 offset:20480
	ds_read_b128 v[164:167], v227 offset:21504
	ds_read_b128 v[192:195], v227 offset:22528
	ds_read_b128 v[196:199], v227 offset:23552
	global_load_lds_dwordx4 v[216:217], off
	v_lshl_add_u64 v[238:239], s[12:13], 0, v[184:185]
	s_mov_b32 m0, s55
	s_nop 0
	global_load_lds_dwordx4 v[238:239], off
	s_barrier
	s_waitcnt lgkmcnt(0)
	s_setprio 1
	s_waitcnt lgkmcnt(0)
	v_mfma_f32_16x16x32_bf16 v[60:63], v[64:67], v[108:111], v[60:63]
	v_mfma_f32_16x16x32_bf16 v[56:59], v[72:75], v[108:111], v[56:59]
	v_mfma_f32_16x16x32_bf16 v[52:55], v[64:67], v[116:119], v[52:55]
	v_mfma_f32_16x16x32_bf16 v[48:51], v[72:75], v[116:119], v[48:51]
	v_mfma_f32_16x16x32_bf16 v[44:47], v[64:67], v[160:163], v[44:47]
	v_mfma_f32_16x16x32_bf16 v[40:43], v[72:75], v[160:163], v[40:43]
	v_mfma_f32_16x16x32_bf16 v[36:39], v[64:67], v[192:195], v[36:39]
	v_mfma_f32_16x16x32_bf16 v[32:35], v[72:75], v[192:195], v[32:35]
	v_mfma_f32_16x16x32_bf16 v[60:63], v[68:71], v[112:115], v[60:63]
	v_mfma_f32_16x16x32_bf16 v[56:59], v[76:79], v[112:115], v[56:59]
	v_mfma_f32_16x16x32_bf16 v[52:55], v[68:71], v[120:123], v[52:55]
	v_mfma_f32_16x16x32_bf16 v[48:51], v[76:79], v[120:123], v[48:51]
	v_mfma_f32_16x16x32_bf16 v[44:47], v[68:71], v[164:167], v[44:47]
	v_mfma_f32_16x16x32_bf16 v[40:43], v[76:79], v[164:167], v[40:43]
	v_mfma_f32_16x16x32_bf16 v[36:39], v[68:71], v[196:199], v[36:39]
	v_mfma_f32_16x16x32_bf16 v[32:35], v[76:79], v[196:199], v[32:35]
	s_setprio 0
	s_barrier
	s_add_u32 s76, s10, 0x100000
	s_addc_u32 s77, s11, 0
	s_add_i32 s45, s78, s47
	v_lshl_add_u64 v[64:65], s[76:77], 0, v[174:175]
	s_mov_b32 m0, s45
	s_nop 0
	global_load_lds_dwordx4 v[64:65], off
	v_lshl_add_u64 v[64:65], s[76:77], 0, v[182:183]
	s_add_i32 m0, s45, 0x2000
	s_nop 0
	global_load_lds_dwordx4 v[64:65], off
	s_waitcnt vmcnt(6)
	s_barrier
	s_setprio 1
	v_mfma_f32_16x16x32_bf16 v[28:31], v[200:203], v[108:111], v[28:31]
	v_mfma_f32_16x16x32_bf16 v[24:27], v[208:211], v[108:111], v[24:27]
	v_mfma_f32_16x16x32_bf16 v[20:23], v[200:203], v[116:119], v[20:23]
	v_mfma_f32_16x16x32_bf16 v[16:19], v[208:211], v[116:119], v[16:19]
	v_mfma_f32_16x16x32_bf16 v[12:15], v[200:203], v[160:163], v[12:15]
	v_mfma_f32_16x16x32_bf16 v[8:11], v[208:211], v[160:163], v[8:11]
	v_mfma_f32_16x16x32_bf16 v[4:7], v[200:203], v[192:195], v[4:7]
	v_mfma_f32_16x16x32_bf16 v[0:3], v[208:211], v[192:195], v[0:3]
	v_mfma_f32_16x16x32_bf16 v[28:31], v[204:207], v[112:115], v[28:31]
	v_mfma_f32_16x16x32_bf16 v[24:27], v[212:215], v[112:115], v[24:27]
	v_mfma_f32_16x16x32_bf16 v[20:23], v[204:207], v[120:123], v[20:23]
	v_mfma_f32_16x16x32_bf16 v[16:19], v[212:215], v[120:123], v[16:19]
	v_mfma_f32_16x16x32_bf16 v[12:15], v[204:207], v[164:167], v[12:15]
	v_mfma_f32_16x16x32_bf16 v[8:11], v[212:215], v[164:167], v[8:11]
	v_mfma_f32_16x16x32_bf16 v[4:7], v[204:207], v[196:199], v[4:7]
	v_mfma_f32_16x16x32_bf16 v[0:3], v[212:215], v[196:199], v[0:3]
	s_setprio 0
	s_add_i32 s45, 0, 0x18000
	v_add_u32_e32 v76, s45, v222
	s_barrier
	ds_read_b128 v[64:67], v76
	ds_read_b128 v[68:71], v76 offset:1024
	ds_read_b128 v[72:75], v76 offset:2048
	ds_read_b128 v[76:79], v76 offset:3072
	s_add_u32 s12, s12, 0x100000
	s_addc_u32 s13, s13, 0
	s_mov_b32 m0, s58
	v_lshl_add_u64 v[116:117], s[12:13], 0, v[186:187]
	ds_read_b128 v[108:111], v227 offset:32768
	ds_read_b128 v[112:115], v227 offset:33792
	ds_read_b128 v[160:163], v227 offset:34816
	ds_read_b128 v[164:167], v227 offset:35840
	ds_read_b128 v[192:195], v227 offset:36864
	ds_read_b128 v[196:199], v227 offset:37888
	ds_read_b128 v[200:203], v227 offset:38912
	ds_read_b128 v[204:207], v227 offset:39936
	global_load_lds_dwordx4 v[116:117], off
	v_lshl_add_u64 v[116:117], s[12:13], 0, v[184:185]
	s_mov_b32 m0, s59
	s_nop 0
	global_load_lds_dwordx4 v[116:117], off
	s_waitcnt lgkmcnt(8)
	s_barrier
	s_waitcnt lgkmcnt(0)
	s_setprio 1
	s_waitcnt lgkmcnt(0)
	v_mfma_f32_16x16x32_bf16 v[116:119], v[64:67], v[108:111], v[156:159]
	v_mfma_f32_16x16x32_bf16 v[156:159], v[68:71], v[112:115], v[116:119]
	v_mfma_f32_16x16x32_bf16 v[116:119], v[72:75], v[108:111], v[152:155]
	v_mfma_f32_16x16x32_bf16 v[152:155], v[76:79], v[112:115], v[116:119]
	v_mfma_f32_16x16x32_bf16 v[116:119], v[64:67], v[160:163], v[148:151]
	v_mfma_f32_16x16x32_bf16 v[148:151], v[68:71], v[164:167], v[116:119]
	v_mfma_f32_16x16x32_bf16 v[116:119], v[72:75], v[160:163], v[144:147]
	v_mfma_f32_16x16x32_bf16 v[144:147], v[76:79], v[164:167], v[116:119]
	v_mfma_f32_16x16x32_bf16 v[116:119], v[64:67], v[192:195], v[140:143]
	v_mfma_f32_16x16x32_bf16 v[140:143], v[68:71], v[196:199], v[116:119]
	v_mfma_f32_16x16x32_bf16 v[116:119], v[72:75], v[192:195], v[136:139]
	v_mfma_f32_16x16x32_bf16 v[136:139], v[76:79], v[196:199], v[116:119]
	v_mfma_f32_16x16x32_bf16 v[116:119], v[64:67], v[200:203], v[132:135]
	v_mfma_f32_16x16x32_bf16 v[132:135], v[68:71], v[204:207], v[116:119]
	v_mfma_f32_16x16x32_bf16 v[116:119], v[72:75], v[200:203], v[128:131]
	v_mfma_f32_16x16x32_bf16 v[128:131], v[76:79], v[204:207], v[116:119]
	s_setprio 0
	s_barrier
	s_add_i32 s12, 0, 0x1c000
	s_nop 3
	v_add_u32_e32 v116, s12, v222
	s_add_i32 s13, s45, s47
	ds_read_b128 v[208:211], v116
	ds_read_b128 v[212:215], v116 offset:1024
	ds_read_b128 v[228:231], v116 offset:2048
	ds_read_b128 v[232:235], v116 offset:3072
	v_lshl_add_u64 v[116:117], v[168:169], 0, s[8:9]
	s_mov_b32 m0, s13
	s_nop 0
	global_load_lds_dwordx4 v[116:117], off
	v_lshl_add_u64 v[116:117], v[172:173], 0, s[8:9]
	s_add_i32 m0, s13, 0x2000
	s_nop 0
	global_load_lds_dwordx4 v[116:117], off
	s_barrier
	s_waitcnt lgkmcnt(0)
	s_setprio 1
	s_waitcnt lgkmcnt(0)
	v_mfma_f32_16x16x32_bf16 v[96:99], v[228:231], v[108:111], v[96:99]
	v_mfma_f32_16x16x32_bf16 v[116:119], v[208:211], v[108:111], v[124:127]
	v_mfma_f32_16x16x32_bf16 v[120:123], v[232:235], v[112:115], v[96:99]
	v_mfma_f32_16x16x32_bf16 v[96:99], v[208:211], v[160:163], v[100:103]
	v_mfma_f32_16x16x32_bf16 v[124:127], v[212:215], v[112:115], v[116:119]
	v_mfma_f32_16x16x32_bf16 v[116:119], v[212:215], v[164:167], v[96:99]
	v_mfma_f32_16x16x32_bf16 v[96:99], v[228:231], v[160:163], v[104:107]
	v_mfma_f32_16x16x32_bf16 v[92:95], v[208:211], v[192:195], v[92:95]
	v_mfma_f32_16x16x32_bf16 v[88:91], v[228:231], v[192:195], v[88:91]
	v_mfma_f32_16x16x32_bf16 v[84:87], v[208:211], v[200:203], v[84:87]
	v_mfma_f32_16x16x32_bf16 v[80:83], v[228:231], v[200:203], v[80:83]
	v_mfma_f32_16x16x32_bf16 v[112:115], v[232:235], v[164:167], v[96:99]
	v_mfma_f32_16x16x32_bf16 v[92:95], v[212:215], v[196:199], v[92:95]
	v_mfma_f32_16x16x32_bf16 v[88:91], v[232:235], v[196:199], v[88:91]
	v_mfma_f32_16x16x32_bf16 v[84:87], v[212:215], v[204:207], v[84:87]
	v_mfma_f32_16x16x32_bf16 v[80:83], v[232:235], v[204:207], v[80:83]
	s_setprio 0
	s_mov_b32 m0, s62
	v_lshl_add_u64 v[168:169], v[216:217], 0, s[8:9]
	s_barrier
	ds_read_b128 v[96:99], v227 offset:49152
	ds_read_b128 v[100:103], v227 offset:50176
	ds_read_b128 v[104:107], v227 offset:51200
	ds_read_b128 v[108:111], v227 offset:52224
	ds_read_b128 v[160:163], v227 offset:53248
	ds_read_b128 v[164:167], v227 offset:54272
	ds_read_b128 v[192:195], v227 offset:55296
	ds_read_b128 v[196:199], v227 offset:56320
	global_load_lds_dwordx4 v[168:169], off
	v_lshl_add_u64 v[168:169], v[238:239], 0, s[8:9]
	s_mov_b32 m0, s63
	s_nop 0
	global_load_lds_dwordx4 v[168:169], off
	s_barrier
	s_waitcnt lgkmcnt(0)
	s_setprio 1
	s_waitcnt lgkmcnt(0)
	v_mfma_f32_16x16x32_bf16 v[60:63], v[64:67], v[96:99], v[60:63]
	v_mfma_f32_16x16x32_bf16 v[56:59], v[72:75], v[96:99], v[56:59]
	v_mfma_f32_16x16x32_bf16 v[52:55], v[64:67], v[104:107], v[52:55]
	v_mfma_f32_16x16x32_bf16 v[48:51], v[72:75], v[104:107], v[48:51]
	v_mfma_f32_16x16x32_bf16 v[44:47], v[64:67], v[160:163], v[44:47]
	v_mfma_f32_16x16x32_bf16 v[40:43], v[72:75], v[160:163], v[40:43]
	v_mfma_f32_16x16x32_bf16 v[36:39], v[64:67], v[192:195], v[36:39]
	v_mfma_f32_16x16x32_bf16 v[32:35], v[72:75], v[192:195], v[32:35]
	v_mfma_f32_16x16x32_bf16 v[60:63], v[68:71], v[100:103], v[60:63]
	v_mfma_f32_16x16x32_bf16 v[56:59], v[76:79], v[100:103], v[56:59]
	v_mfma_f32_16x16x32_bf16 v[52:55], v[68:71], v[108:111], v[52:55]
	v_mfma_f32_16x16x32_bf16 v[48:51], v[76:79], v[108:111], v[48:51]
	v_mfma_f32_16x16x32_bf16 v[44:47], v[68:71], v[164:167], v[44:47]
	v_mfma_f32_16x16x32_bf16 v[40:43], v[76:79], v[164:167], v[40:43]
	v_mfma_f32_16x16x32_bf16 v[36:39], v[68:71], v[196:199], v[36:39]
	v_mfma_f32_16x16x32_bf16 v[32:35], v[76:79], v[196:199], v[32:35]
	s_setprio 0
	s_barrier
	s_add_u32 s10, s10, 0x100080
	s_addc_u32 s11, s11, 0
	s_add_i32 s12, s12, s47
	v_lshl_add_u64 v[64:65], s[10:11], 0, v[174:175]
	s_mov_b32 m0, s12
	s_nop 0
	global_load_lds_dwordx4 v[64:65], off
	v_lshl_add_u64 v[64:65], s[10:11], 0, v[182:183]
	s_add_i32 m0, s12, 0x2000
	s_nop 0
	global_load_lds_dwordx4 v[64:65], off
	s_waitcnt vmcnt(6)
	s_barrier
	s_setprio 1
	v_mfma_f32_16x16x32_bf16 v[28:31], v[208:211], v[96:99], v[28:31]
	v_mfma_f32_16x16x32_bf16 v[24:27], v[228:231], v[96:99], v[24:27]
	v_mfma_f32_16x16x32_bf16 v[20:23], v[208:211], v[104:107], v[20:23]
	v_mfma_f32_16x16x32_bf16 v[16:19], v[228:231], v[104:107], v[16:19]
	v_mfma_f32_16x16x32_bf16 v[12:15], v[208:211], v[160:163], v[12:15]
	v_mfma_f32_16x16x32_bf16 v[8:11], v[228:231], v[160:163], v[8:11]
	v_mfma_f32_16x16x32_bf16 v[4:7], v[208:211], v[192:195], v[4:7]
	v_mfma_f32_16x16x32_bf16 v[0:3], v[228:231], v[192:195], v[0:3]
	v_mfma_f32_16x16x32_bf16 v[28:31], v[212:215], v[100:103], v[28:31]
	v_mfma_f32_16x16x32_bf16 v[24:27], v[232:235], v[100:103], v[24:27]
	v_mfma_f32_16x16x32_bf16 v[20:23], v[212:215], v[108:111], v[20:23]
	v_mfma_f32_16x16x32_bf16 v[16:19], v[232:235], v[108:111], v[16:19]
	v_mfma_f32_16x16x32_bf16 v[12:15], v[212:215], v[164:167], v[12:15]
	v_mfma_f32_16x16x32_bf16 v[8:11], v[232:235], v[164:167], v[8:11]
	v_mfma_f32_16x16x32_bf16 v[4:7], v[212:215], v[196:199], v[4:7]
	v_mfma_f32_16x16x32_bf16 v[0:3], v[232:235], v[196:199], v[0:3]
	s_setprio 0
	s_add_i32 s44, s44, 2
	s_add_u32 s42, s42, 0x100
	s_addc_u32 s43, s43, 0
	s_add_u32 s35, s35, 0x100
	s_addc_u32 s37, s37, 0
	s_cmp_gt_u32 s44, 61
	s_barrier
	s_cbranch_scc0 .LBB0_1351
	s_nop 15
	s_nop 15
	s_waitcnt vmcnt(6)
	v_lshl_add_u32 v64, v237, 4, s47
	v_add_u32_e32 v65, 0x10000, v64
	ds_write_b128 v64, v[0:3] offset:49152
	ds_write_b128 v64, v[4:7] offset:57344
	ds_write_b128 v65, v[8:11]
	ds_write_b128 v65, v[12:15] offset:8192
	ds_write_b128 v64, v[16:19]
	ds_write_b128 v64, v[20:23] offset:8192
	ds_write_b128 v65, v[24:27] offset:16384
	ds_write_b128 v65, v[28:31] offset:24576
	s_mov_b64 s[10:11], s[0:1]
	s_load_dwordx4 s[76:79], s[10:11], 0x98
	s_load_dwordx2 s[44:45], s[10:11], 0xd0
	s_mov_b32 s10, s74
	s_lshl_b32 s10, s10, 10
	s_ashr_i32 s11, s10, 31
	s_lshl_b64 s[10:11], s[10:11], 2
	s_waitcnt lgkmcnt(0)
	s_add_u32 s12, s76, s10
	s_addc_u32 s13, s77, s11
	s_add_u32 s10, s78, s10
	s_addc_u32 s11, s79, s11
	s_lshl_b32 s16, s26, 11
	v_lshl_add_u32 v192, s27, 8, v221
	v_lshl_or_b32 v196, s75, 8, v223
	s_add_u32 s42, s44, 0x2a00000
	v_ashrrev_i32_e32 v193, 31, v192
	v_ashrrev_i32_e32 v197, 31, v196
	s_addc_u32 s43, s45, 0
	v_lshlrev_b64 v[230:231], 11, v[192:193]
	v_or_b32_e32 v198, 16, v192
	v_lshl_add_u64 v[202:203], s[42:43], 0, v[230:231]
	v_lshlrev_b64 v[64:65], 1, v[196:197]
	v_ashrrev_i32_e32 v199, 31, v198
	v_lshl_add_u64 v[208:209], v[202:203], 0, v[64:65]
	v_lshl_add_u64 v[194:195], s[42:43], 0, v[64:65]
	v_lshlrev_b64 v[210:211], 11, v[198:199]
	v_lshl_add_u64 v[234:235], v[194:195], 0, v[210:211]
	v_lshlrev_b64 v[64:65], 2, v[196:197]
	v_lshl_add_u64 v[76:77], s[10:11], 0, v[64:65]
	v_lshl_add_u64 v[68:69], s[12:13], 0, v[64:65]
	global_load_dwordx4 v[96:99], v[76:77], off
	global_load_dwordx4 v[100:103], v[68:69], off
	global_load_dwordx4 v[104:107], v[68:69], off offset:16
	global_load_dwordx4 v[108:111], v[76:77], off offset:16
	v_add_u32_e32 v228, s16, v224
	global_load_dwordx4 v[64:67], v[68:69], off offset:528
	global_load_dwordx4 v[72:75], v[68:69], off offset:512
	s_nop 0
	global_load_dwordx4 v[68:71], v[76:77], off offset:528
	s_nop 0
	global_load_dwordx4 v[76:79], v[76:77], off offset:512
	s_waitcnt lgkmcnt(0)
	s_mov_b32 s101, 0
	s_mov_b32 s100, 0x8000
	v_lshl_add_u64 v[160:161], v[208:209], 0, s[100:101]
	s_mov_b32 s100, 0x10000
	v_lshl_add_u64 v[162:163], v[208:209], 0, s[100:101]
	s_mov_b32 s100, 0x18000
	v_lshl_add_u64 v[164:165], v[208:209], 0, s[100:101]
	global_load_dwordx4 v[0:3], v[208:209], off
	global_load_dwordx4 v[4:7], v[160:161], off
	global_load_dwordx4 v[8:11], v[162:163], off
	global_load_dwordx4 v[12:15], v[164:165], off
	global_load_dwordx4 v[16:19], v[208:209], off offset:256
	global_load_dwordx4 v[20:23], v[160:161], off offset:256
	global_load_dwordx4 v[24:27], v[162:163], off offset:256
	global_load_dwordx4 v[28:31], v[164:165], off offset:256
	ds_read2_b64 v[164:167], v228 offset1:16
	ds_read2_b64 v[160:163], v228 offset0:32 offset1:48
	v_lshl_add_u64 v[244:245], v[194:195], 0, v[230:231]
	v_or_b32_e32 v200, 32, v192
	v_ashrrev_i32_e32 v201, 31, v200
	v_lshlrev_b64 v[212:213], 11, v[200:201]
	v_lshl_add_u64 v[252:253], v[194:195], 0, v[212:213]
	s_lshl_b32 s10, s75, 3
	s_or_b32 s10, s10, s68
	s_ashr_i32 s11, s10, 31
	s_lshl_b64 s[10:11], s[10:11], 2
	s_add_u32 s10, s44, s10
	s_addc_u32 s11, s45, s11
	s_add_u32 s44, s10, 0xed84000
	s_addc_u32 s45, s11, 0
	s_waitcnt vmcnt(7)
	s_nop 1
	v_mov_b32_e32 v204, v0
	v_mov_b32_e32 v205, v1
	v_mov_b32_e32 v206, v2
	v_mov_b32_e32 v207, v3
	v_lshlrev_b32_e32 v168, 16, v204
	v_and_b32_e32 v169, 0xffff0000, v204
	v_lshlrev_b32_e32 v172, 16, v205
	v_and_b32_e32 v173, 0xffff0000, v205
	v_lshlrev_b32_e32 v229, 16, v206
	v_and_b32_e32 v230, 0xffff0000, v206
	v_lshlrev_b32_e32 v231, 16, v207
	v_and_b32_e32 v232, 0xffff0000, v207
	s_waitcnt vmcnt(6)
	s_nop 1
	v_mov_b32_e32 v214, v4
	v_mov_b32_e32 v215, v5
	v_mov_b32_e32 v216, v6
	v_mov_b32_e32 v217, v7
	v_lshlrev_b32_e32 v233, 16, v214
	v_and_b32_e32 v238, 0xffff0000, v214
	v_lshlrev_b32_e32 v239, 16, v215
	v_and_b32_e32 v246, 0xffff0000, v215
	s_waitcnt lgkmcnt(1)
	v_sub_f32_e32 v205, v169, v164
	v_sub_f32_e32 v204, v168, v164
	v_sub_f32_e32 v207, v173, v164
	v_sub_f32_e32 v206, v172, v164
	v_sub_f32_e32 v215, v230, v164
	v_sub_f32_e32 v214, v229, v164
	v_lshlrev_b32_e32 v247, 16, v216
	v_and_b32_e32 v248, 0xffff0000, v216
	v_lshlrev_b32_e32 v249, 16, v217
	v_and_b32_e32 v250, 0xffff0000, v217
	v_sub_f32_e32 v217, v232, v164
	v_sub_f32_e32 v216, v231, v164
	v_pk_mul_f32 v[206:207], v[164:165], v[206:207] op_sel:[1,0]
	v_pk_mul_f32 v[204:205], v[164:165], v[204:205] op_sel:[1,0]
	v_pk_mul_f32 v[214:215], v[164:165], v[214:215] op_sel:[1,0]
	v_pk_mul_f32 v[216:217], v[164:165], v[216:217] op_sel:[1,0]
	v_pk_fma_f32 v[204:205], v[100:101], v[204:205], v[96:97]
	v_pk_fma_f32 v[206:207], v[102:103], v[206:207], v[98:99]
	v_pk_fma_f32 v[214:215], v[104:105], v[214:215], v[108:109]
	v_pk_fma_f32 v[216:217], v[106:107], v[216:217], v[110:111]
	v_pk_fma_f32 v[158:159], v[206:207], s[70:71], v[158:159] op_sel_hi:[1,0,1]
	v_pk_fma_f32 v[206:207], v[204:205], s[70:71], v[156:157] op_sel_hi:[1,0,1]
	v_pk_fma_f32 v[204:205], v[214:215], s[70:71], v[152:153] op_sel_hi:[1,0,1]
	v_cvt_pk_bf16_f32 v152, v206, v207
	v_cvt_pk_bf16_f32 v153, v158, v159
	v_pk_fma_f32 v[156:157], v[216:217], s[70:71], v[154:155] op_sel_hi:[1,0,1]
	v_cvt_pk_bf16_f32 v154, v204, v205
	v_sub_f32_e32 v231, v238, v166
	v_cvt_pk_bf16_f32 v155, v156, v157
	global_store_dwordx4 v[244:245], v[152:155], off
	v_sub_f32_e32 v230, v233, v166
	v_sub_f32_e32 v233, v246, v166
	v_sub_f32_e32 v153, v248, v166
	v_sub_f32_e32 v152, v247, v166
	v_pk_mul_f32 v[152:153], v[166:167], v[152:153] op_sel:[1,0]
	v_sub_f32_e32 v232, v239, v166
	v_pk_fma_f32 v[152:153], v[104:105], v[152:153], v[108:109]
	v_pk_mul_f32 v[232:233], v[166:167], v[232:233] op_sel:[1,0]
	v_pk_fma_f32 v[152:153], v[152:153], s[70:71], v[144:145] op_sel_hi:[1,0,1]
	v_or_b32_e32 v144, 48, v192
	v_pk_mul_f32 v[230:231], v[166:167], v[230:231] op_sel:[1,0]
	v_sub_f32_e32 v155, v250, v166
	v_sub_f32_e32 v154, v249, v166
	v_ashrrev_i32_e32 v145, 31, v144
	v_pk_fma_f32 v[230:231], v[100:101], v[230:231], v[96:97]
	v_pk_fma_f32 v[232:233], v[102:103], v[232:233], v[98:99]
	v_pk_mul_f32 v[154:155], v[166:167], v[154:155] op_sel:[1,0]
	v_lshlrev_b64 v[216:217], 11, v[144:145]
	v_pk_fma_f32 v[150:151], v[232:233], s[70:71], v[150:151] op_sel_hi:[1,0,1]
	v_pk_fma_f32 v[148:149], v[230:231], s[70:71], v[148:149] op_sel_hi:[1,0,1]
	v_pk_fma_f32 v[154:155], v[106:107], v[154:155], v[110:111]
	v_lshl_add_u64 v[214:215], v[194:195], 0, v[216:217]
	v_pk_fma_f32 v[146:147], v[154:155], s[70:71], v[146:147] op_sel_hi:[1,0,1]
	v_cvt_pk_bf16_f32 v244, v148, v149
	v_cvt_pk_bf16_f32 v245, v150, v151
	v_cvt_pk_bf16_f32 v246, v152, v153
	s_waitcnt vmcnt(6)
	s_nop 1
	v_mov_b32_e32 v230, v8
	v_mov_b32_e32 v231, v9
	v_mov_b32_e32 v232, v10
	v_mov_b32_e32 v233, v11
	v_lshlrev_b32_e32 v154, 16, v230
	v_cvt_pk_bf16_f32 v247, v146, v147
	v_and_b32_e32 v155, 0xffff0000, v230
	global_store_dwordx4 v[234:235], v[244:247], off
	v_lshlrev_b32_e32 v168, 16, v231
	v_and_b32_e32 v169, 0xffff0000, v231
	v_lshlrev_b32_e32 v172, 16, v232
	v_and_b32_e32 v173, 0xffff0000, v232
	v_lshlrev_b32_e32 v229, 16, v233
	v_and_b32_e32 v234, 0xffff0000, v233
	s_waitcnt lgkmcnt(0)
	v_sub_f32_e32 v155, v155, v160
	v_sub_f32_e32 v154, v154, v160
	v_sub_f32_e32 v231, v169, v160
	v_sub_f32_e32 v230, v168, v160
	v_sub_f32_e32 v233, v173, v160
	v_sub_f32_e32 v232, v172, v160
	v_sub_f32_e32 v235, v234, v160
	v_sub_f32_e32 v234, v229, v160
	v_pk_mul_f32 v[154:155], v[160:161], v[154:155] op_sel:[1,0]
	v_pk_mul_f32 v[232:233], v[160:161], v[232:233] op_sel:[1,0]
	v_pk_fma_f32 v[154:155], v[100:101], v[154:155], v[96:97]
	v_pk_fma_f32 v[232:233], v[104:105], v[232:233], v[108:109]
	v_pk_mul_f32 v[230:231], v[160:161], v[230:231] op_sel:[1,0]
	v_pk_mul_f32 v[234:235], v[160:161], v[234:235] op_sel:[1,0]
	v_pk_fma_f32 v[154:155], v[154:155], s[70:71], v[140:141] op_sel_hi:[1,0,1]
	v_pk_fma_f32 v[140:141], v[232:233], s[70:71], v[136:137] op_sel_hi:[1,0,1]
	v_pk_fma_f32 v[230:231], v[102:103], v[230:231], v[98:99]
	v_pk_fma_f32 v[234:235], v[106:107], v[234:235], v[110:111]
	v_pk_fma_f32 v[142:143], v[230:231], s[70:71], v[142:143] op_sel_hi:[1,0,1]
	v_pk_fma_f32 v[138:139], v[234:235], s[70:71], v[138:139] op_sel_hi:[1,0,1]
	v_cvt_pk_bf16_f32 v230, v154, v155
	v_cvt_pk_bf16_f32 v231, v142, v143
	v_cvt_pk_bf16_f32 v232, v140, v141
	s_waitcnt vmcnt(6)
	s_nop 1
	v_mov_b32_e32 v248, v12
	v_mov_b32_e32 v249, v13
	v_mov_b32_e32 v250, v14
	v_mov_b32_e32 v251, v15
	v_lshlrev_b32_e32 v168, 16, v248
	v_and_b32_e32 v169, 0xffff0000, v248
	v_lshlrev_b32_e32 v229, 16, v250
	v_and_b32_e32 v238, 0xffff0000, v250
	v_lshlrev_b32_e32 v172, 16, v249
	v_and_b32_e32 v173, 0xffff0000, v249
	v_sub_f32_e32 v245, v169, v162
	v_sub_f32_e32 v244, v168, v162
	v_sub_f32_e32 v249, v238, v162
	v_sub_f32_e32 v248, v229, v162
	v_lshlrev_b32_e32 v239, 16, v251
	v_and_b32_e32 v250, 0xffff0000, v251
	v_pk_mul_f32 v[244:245], v[162:163], v[244:245] op_sel:[1,0]
	v_pk_mul_f32 v[248:249], v[162:163], v[248:249] op_sel:[1,0]
	v_sub_f32_e32 v247, v173, v162
	v_sub_f32_e32 v246, v172, v162
	v_sub_f32_e32 v251, v250, v162
	v_sub_f32_e32 v250, v239, v162
	v_pk_fma_f32 v[136:137], v[100:101], v[244:245], v[96:97]
	v_pk_fma_f32 v[244:245], v[104:105], v[248:249], v[108:109]
	v_pk_mul_f32 v[246:247], v[162:163], v[246:247] op_sel:[1,0]
	v_pk_mul_f32 v[250:251], v[162:163], v[250:251] op_sel:[1,0]
	v_pk_fma_f32 v[132:133], v[136:137], s[70:71], v[132:133] op_sel_hi:[1,0,1]
	v_pk_fma_f32 v[136:137], v[244:245], s[70:71], v[128:129] op_sel_hi:[1,0,1]
	v_or_b32_e32 v128, 0x80, v196
	v_pk_fma_f32 v[234:235], v[102:103], v[246:247], v[98:99]
	v_pk_fma_f32 v[246:247], v[106:107], v[250:251], v[110:111]
	v_cvt_pk_bf16_f32 v233, v138, v139
	v_ashrrev_i32_e32 v129, 31, v128
	v_pk_fma_f32 v[134:135], v[234:235], s[70:71], v[134:135] op_sel_hi:[1,0,1]
	v_pk_fma_f32 v[130:131], v[246:247], s[70:71], v[130:131] op_sel_hi:[1,0,1]
	global_store_dwordx4 v[252:253], v[230:233], off
	v_lshlrev_b64 v[128:129], 1, v[128:129]
	v_mul_f32_e32 v253, v204, v204
	v_cvt_pk_bf16_f32 v230, v132, v133
	v_cvt_pk_bf16_f32 v231, v134, v135
	v_cvt_pk_bf16_f32 v232, v136, v137
	v_cvt_pk_bf16_f32 v233, v130, v131
	v_lshl_add_u64 v[208:209], s[42:43], 0, v[210:211]
	v_lshl_add_u64 v[208:209], v[208:209], 0, v[128:129]
	v_lshl_add_u64 v[210:211], s[42:43], 0, v[212:213]
	v_lshl_add_u64 v[212:213], s[42:43], 0, v[216:217]
	global_store_dwordx4 v[214:215], v[230:233], off
	v_lshl_add_u64 v[216:217], v[202:203], 0, v[128:129]
	v_lshl_add_u64 v[202:203], v[212:213], 0, v[128:129]
	v_lshl_add_u64 v[210:211], v[210:211], 0, v[128:129]
	s_waitcnt vmcnt(7)
	s_nop 1
	v_mov_b32_e32 v244, v16
	v_mov_b32_e32 v245, v17
	v_mov_b32_e32 v246, v18
	v_mov_b32_e32 v247, v19
	v_lshlrev_b32_e32 v168, 16, v244
	v_and_b32_e32 v169, 0xffff0000, v244
	v_lshlrev_b32_e32 v172, 16, v245
	v_and_b32_e32 v173, 0xffff0000, v245
	v_lshlrev_b32_e32 v229, 16, v246
	v_and_b32_e32 v230, 0xffff0000, v246
	v_lshlrev_b32_e32 v232, 16, v247
	v_and_b32_e32 v233, 0xffff0000, v247
	v_sub_f32_e32 v213, v169, v164
	v_sub_f32_e32 v212, v168, v164
	v_sub_f32_e32 v215, v173, v164
	v_sub_f32_e32 v214, v172, v164
	v_sub_f32_e32 v231, v230, v164
	v_sub_f32_e32 v230, v229, v164
	v_sub_f32_e32 v233, v233, v164
	v_sub_f32_e32 v232, v232, v164
	s_waitcnt vmcnt(6)
	s_nop 1
	v_mov_b32_e32 v248, v20
	v_mov_b32_e32 v249, v21
	v_mov_b32_e32 v250, v22
	v_mov_b32_e32 v251, v23
	v_lshlrev_b32_e32 v234, 16, v248
	v_and_b32_e32 v235, 0xffff0000, v248
	v_lshlrev_b32_e32 v238, 16, v249
	v_and_b32_e32 v239, 0xffff0000, v249
	v_lshlrev_b32_e32 v246, 16, v250
	v_and_b32_e32 v247, 0xffff0000, v250
	v_lshlrev_b32_e32 v248, 16, v251
	v_and_b32_e32 v249, 0xffff0000, v251
	v_pk_mul_f32 v[214:215], v[164:165], v[214:215] op_sel:[1,0]
	v_pk_mul_f32 v[212:213], v[164:165], v[212:213] op_sel:[1,0]
	v_pk_mul_f32 v[232:233], v[164:165], v[232:233] op_sel:[1,0]
	v_pk_mul_f32 v[164:165], v[164:165], v[230:231] op_sel:[1,0]
	v_sub_f32_e32 v235, v235, v166
	v_sub_f32_e32 v234, v234, v166
	v_sub_f32_e32 v245, v239, v166
	v_sub_f32_e32 v244, v238, v166
	v_sub_f32_e32 v247, v247, v166
	v_sub_f32_e32 v246, v246, v166
	v_sub_f32_e32 v249, v249, v166
	v_sub_f32_e32 v248, v248, v166
	v_pk_fma_f32 v[212:213], v[72:73], v[212:213], v[76:77]
	v_pk_fma_f32 v[214:215], v[74:75], v[214:215], v[78:79]
	v_pk_fma_f32 v[164:165], v[64:65], v[164:165], v[68:69]
	v_pk_fma_f32 v[232:233], v[66:67], v[232:233], v[70:71]
	v_pk_mul_f32 v[230:231], v[166:167], v[244:245] op_sel:[1,0]
	v_pk_mul_f32 v[234:235], v[166:167], v[234:235] op_sel:[1,0]
	v_pk_fma_f32 v[214:215], v[214:215], s[70:71], v[126:127] op_sel_hi:[1,0,1]
	v_pk_fma_f32 v[212:213], v[212:213], s[70:71], v[124:125] op_sel_hi:[1,0,1]
	v_pk_fma_f32 v[232:233], v[232:233], s[70:71], v[122:123] op_sel_hi:[1,0,1]
	v_pk_fma_f32 v[244:245], v[164:165], s[70:71], v[120:121] op_sel_hi:[1,0,1]
	v_cvt_pk_bf16_f32 v120, v212, v213
	v_cvt_pk_bf16_f32 v121, v214, v215
	v_pk_mul_f32 v[164:165], v[166:167], v[248:249] op_sel:[1,0]
	v_cvt_pk_bf16_f32 v122, v244, v245
	v_cvt_pk_bf16_f32 v123, v232, v233
	v_pk_mul_f32 v[166:167], v[166:167], v[246:247] op_sel:[1,0]
	v_pk_fma_f32 v[234:235], v[72:73], v[234:235], v[76:77]
	v_pk_fma_f32 v[230:231], v[74:75], v[230:231], v[78:79]
	v_pk_fma_f32 v[166:167], v[64:65], v[166:167], v[68:69]
	v_pk_fma_f32 v[164:165], v[66:67], v[164:165], v[70:71]
	v_pk_fma_f32 v[118:119], v[230:231], s[70:71], v[118:119] op_sel_hi:[1,0,1]
	v_pk_fma_f32 v[116:117], v[234:235], s[70:71], v[116:117] op_sel_hi:[1,0,1]
	v_pk_fma_f32 v[114:115], v[164:165], s[70:71], v[114:115] op_sel_hi:[1,0,1]
	v_pk_fma_f32 v[112:113], v[166:167], s[70:71], v[112:113] op_sel_hi:[1,0,1]
	global_store_dwordx4 v[216:217], v[120:123], off
	v_add_f32_e32 v230, v158, v159
	v_add_f32_e32 v246, v156, v157
	v_cvt_pk_bf16_f32 v120, v116, v117
	v_cvt_pk_bf16_f32 v121, v118, v119
	v_cvt_pk_bf16_f32 v122, v112, v113
	v_cvt_pk_bf16_f32 v123, v114, v115
	v_mul_f32_e32 v251, v158, v158
	global_store_dwordx4 v[208:209], v[120:123], off
	v_mul_f32_e32 v239, v156, v156
	v_add_f32_e32 v216, v206, v207
	v_mul_f32_e32 v249, v206, v206
	v_mul_f32_e32 v207, v207, v207
	v_mul_f32_e32 v159, v159, v159
	v_pk_mul_f32 v[172:173], v[232:233], v[232:233]
	v_pk_mul_f32 v[168:169], v[244:245], v[244:245]
	v_mov_b32_e32 v248, v212
	v_mov_b32_e32 v206, v213
	v_mov_b32_e32 v250, v214
	v_add_f32_e32 v234, v204, v205
	v_mul_f32_e32 v205, v205, v205
	v_mul_f32_e32 v157, v157, v157
	v_mul_f32_e32 v217, v212, v212
	v_mul_f32_e32 v231, v213, v213
	v_pk_mov_b32 v[212:213], v[168:169], v[172:173] op_sel:[1,0]
	v_mov_b32_e32 v169, v173
	v_mov_b32_e32 v252, v244
	v_mov_b32_e32 v204, v245
	v_mov_b32_e32 v238, v232
	v_pk_add_f32 v[168:169], v[212:213], v[168:169]
	v_mul_f32_e32 v235, v214, v214
	v_mul_f32_e32 v247, v215, v215
	v_pk_add_f32 v[168:169], v[168:169], v[168:169] op_sel_hi:[0,1]
	s_waitcnt vmcnt(7)
	s_nop 1
	v_mov_b32_e32 v124, v24
	v_mov_b32_e32 v125, v25
	v_mov_b32_e32 v126, v26
	v_mov_b32_e32 v127, v27
	v_lshlrev_b32_e32 v120, 16, v124
	v_and_b32_e32 v121, 0xffff0000, v124
	v_lshlrev_b32_e32 v122, 16, v125
	v_and_b32_e32 v123, 0xffff0000, v125
	v_lshlrev_b32_e32 v124, 16, v126
	v_and_b32_e32 v125, 0xffff0000, v126
	v_lshlrev_b32_e32 v126, 16, v127
	v_and_b32_e32 v127, 0xffff0000, v127
	v_sub_f32_e32 v121, v121, v160
	v_sub_f32_e32 v120, v120, v160
	v_sub_f32_e32 v123, v123, v160
	v_sub_f32_e32 v122, v122, v160
	v_sub_f32_e32 v125, v125, v160
	v_sub_f32_e32 v124, v124, v160
	v_sub_f32_e32 v127, v127, v160
	v_sub_f32_e32 v126, v126, v160
	v_pk_mul_f32 v[122:123], v[160:161], v[122:123] op_sel:[1,0]
	s_waitcnt vmcnt(6)
	s_nop 1
	v_mov_b32_e32 v164, v28
	v_mov_b32_e32 v165, v29
	v_mov_b32_e32 v166, v30
	v_mov_b32_e32 v167, v31
	v_lshlrev_b32_e32 v156, 16, v164
	v_and_b32_e32 v158, 0xffff0000, v164
	v_pk_mul_f32 v[120:121], v[160:161], v[120:121] op_sel:[1,0]
	v_pk_mul_f32 v[126:127], v[160:161], v[126:127] op_sel:[1,0]
	v_pk_mul_f32 v[124:125], v[160:161], v[124:125] op_sel:[1,0]
	v_sub_f32_e32 v161, v158, v162
	v_sub_f32_e32 v160, v156, v162
	v_pk_fma_f32 v[120:121], v[72:73], v[120:121], v[76:77]
	v_pk_fma_f32 v[122:123], v[74:75], v[122:123], v[78:79]
	v_pk_fma_f32 v[124:125], v[64:65], v[124:125], v[68:69]
	v_pk_fma_f32 v[126:127], v[66:67], v[126:127], v[70:71]
	v_pk_mul_f32 v[160:161], v[162:163], v[160:161] op_sel:[1,0]
	v_pk_fma_f32 v[94:95], v[122:123], s[70:71], v[94:95] op_sel_hi:[1,0,1]
	v_pk_fma_f32 v[92:93], v[120:121], s[70:71], v[92:93] op_sel_hi:[1,0,1]
	v_pk_fma_f32 v[90:91], v[126:127], s[70:71], v[90:91] op_sel_hi:[1,0,1]
	v_pk_fma_f32 v[88:89], v[124:125], s[70:71], v[88:89] op_sel_hi:[1,0,1]
	v_cvt_pk_bf16_f32 v120, v92, v93
	v_cvt_pk_bf16_f32 v121, v94, v95
	v_mov_b32_e32 v158, v215
	v_cvt_pk_bf16_f32 v122, v88, v89
	v_cvt_pk_bf16_f32 v123, v90, v91
	v_pk_fma_f32 v[124:125], v[72:73], v[160:161], v[76:77]
	global_store_dwordx4 v[210:211], v[120:123], off
	v_mov_b32_e32 v156, v233
	v_pk_fma_f32 v[84:85], v[124:125], s[70:71], v[84:85] op_sel_hi:[1,0,1]
	v_pk_add_f32 v[120:121], v[248:249], v[206:207]
	v_pk_add_f32 v[122:123], v[250:251], v[158:159]
	v_pk_add_f32 v[124:125], v[238:239], v[156:157]
	v_pk_add_f32 v[120:121], v[120:121], v[122:123]
	v_pk_add_f32 v[122:123], v[252:253], v[204:205]
	v_lshlrev_b32_e32 v168, 16, v166
	v_pk_add_f32 v[122:123], v[122:123], v[124:125]
	v_and_b32_e32 v166, 0xffff0000, v166
	v_pk_add_f32 v[120:121], v[120:121], v[122:123]
	v_pk_add_f32 v[122:123], v[216:217], v[230:231]
	v_pk_add_f32 v[124:125], v[234:235], v[246:247]
	v_lshlrev_b32_e32 v172, 16, v167
	v_and_b32_e32 v173, 0xffff0000, v167
	v_sub_f32_e32 v167, v166, v162
	v_sub_f32_e32 v166, v168, v162
	v_pk_add_f32 v[122:123], v[122:123], v[124:125]
	v_mov_b32_e32 v168, v175
	v_pk_add_f32 v[122:123], v[122:123], v[168:169]
	v_lshlrev_b32_e32 v164, 16, v165
	v_pk_add_f32 v[120:121], v[120:121], v[122:123]
	ds_bpermute_b32 v122, v225, v120
	ds_bpermute_b32 v123, v225, v121
	v_and_b32_e32 v165, 0xffff0000, v165
	v_sub_f32_e32 v165, v165, v162
	v_sub_f32_e32 v164, v164, v162
	v_sub_f32_e32 v173, v173, v162
	s_waitcnt lgkmcnt(0)
	v_pk_add_f32 v[120:121], v[120:121], v[122:123]
	ds_bpermute_b32 v122, v226, v120
	ds_bpermute_b32 v123, v226, v121
	v_sub_f32_e32 v172, v172, v162
	v_pk_mul_f32 v[164:165], v[162:163], v[164:165] op_sel:[1,0]
	v_pk_mul_f32 v[172:173], v[162:163], v[172:173] op_sel:[1,0]
	v_pk_mul_f32 v[162:163], v[162:163], v[166:167] op_sel:[1,0]
	v_pk_fma_f32 v[126:127], v[74:75], v[164:165], v[78:79]
	v_pk_fma_f32 v[160:161], v[64:65], v[162:163], v[68:69]
	v_pk_fma_f32 v[124:125], v[66:67], v[172:173], v[70:71]
	v_pk_fma_f32 v[86:87], v[126:127], s[70:71], v[86:87] op_sel_hi:[1,0,1]
	v_pk_fma_f32 v[82:83], v[124:125], s[70:71], v[82:83] op_sel_hi:[1,0,1]
	v_pk_fma_f32 v[80:81], v[160:161], s[70:71], v[80:81] op_sel_hi:[1,0,1]
	v_cvt_pk_bf16_f32 v124, v84, v85
	v_cvt_pk_bf16_f32 v125, v86, v87
	s_nop 0
	v_cvt_pk_bf16_f32 v126, v80, v81
	v_cvt_pk_bf16_f32 v127, v82, v83
	global_store_dwordx4 v[202:203], v[124:127], off
	s_and_saveexec_b64 s[10:11], s[22:23]
	s_cbranch_execz .LBB0_1354
	v_lshlrev_b64 v[124:125], 7, v[192:193]
	v_lshl_add_u64 v[124:125], s[44:45], 0, v[124:125]
	s_waitcnt lgkmcnt(0)
	v_pk_add_f32 v[120:121], v[120:121], v[122:123]
	global_store_dwordx2 v[124:125], v[120:121], off

.LBB0_1360:
	s_or_b64 exec, exec, s[10:11]
	v_add_u32_e32 v94, 0x80, v192
	v_ashrrev_i32_e32 v95, 31, v94
	v_lshlrev_b64 v[118:119], 11, v[94:95]
	v_add_u32_e32 v90, 0x90, v192
	v_lshl_add_u64 v[112:113], s[42:43], 0, v[118:119]
	v_ashrrev_i32_e32 v91, 31, v90
	v_lshl_add_u64 v[114:115], v[196:197], 1, v[112:113]
	v_lshlrev_b64 v[116:117], 11, v[90:91]
	v_lshl_add_u32 v86, v237, 4, s47
	v_add_u32_e32 v87, 0x10000, v86
	ds_read_b128 v[0:3], v86 offset:49152
	ds_read_b128 v[4:7], v86 offset:57344
	ds_read_b128 v[8:11], v87
	ds_read_b128 v[12:15], v87 offset:8192
	ds_read_b128 v[16:19], v86
	ds_read_b128 v[20:23], v86 offset:8192
	ds_read_b128 v[24:27], v87 offset:16384
	ds_read_b128 v[28:31], v87 offset:24576
	s_mov_b32 s101, 0
	s_mov_b32 s100, 0x8000
	v_lshl_add_u64 v[80:81], v[114:115], 0, s[100:101]
	s_mov_b32 s100, 0x10000
	v_lshl_add_u64 v[82:83], v[114:115], 0, s[100:101]
	s_mov_b32 s100, 0x18000
	v_lshl_add_u64 v[84:85], v[114:115], 0, s[100:101]
	global_load_dwordx4 v[156:159], v[114:115], off
	global_load_dwordx4 v[160:163], v[80:81], off
	global_load_dwordx4 v[164:167], v[82:83], off
	global_load_dwordx4 v[196:199], v[84:85], off
	global_load_dwordx4 v[200:203], v[114:115], off offset:256
	global_load_dwordx4 v[204:207], v[80:81], off offset:256
	global_load_dwordx4 v[208:211], v[82:83], off offset:256
	global_load_dwordx4 v[212:215], v[84:85], off offset:256
	s_waitcnt lgkmcnt(0)
	v_lshl_add_u64 v[124:125], v[194:195], 0, v[116:117]
	ds_read2_b64 v[84:87], v228 offset0:128 offset1:144
	s_waitcnt lgkmcnt(1)
	ds_read2_b64 v[80:83], v228 offset0:160 offset1:176
	v_add_u32_e32 v92, 0xa0, v192
	v_ashrrev_i32_e32 v93, 31, v92
	v_lshl_add_u64 v[126:127], v[194:195], 0, v[118:119]
	v_add_u32_e32 v88, 0xb0, v192
	v_lshlrev_b64 v[122:123], 11, v[92:93]
	v_ashrrev_i32_e32 v89, 31, v88
	v_lshl_add_u64 v[138:139], v[194:195], 0, v[122:123]
	v_lshlrev_b64 v[120:121], 11, v[88:89]
	v_lshl_add_u64 v[118:119], v[194:195], 0, v[120:121]
	v_lshl_add_u64 v[112:113], v[112:113], 0, v[128:129]
	s_waitcnt vmcnt(7)
	s_nop 1
	v_mov_b32_e32 v130, v156
	v_mov_b32_e32 v131, v157
	v_mov_b32_e32 v132, v158
	v_mov_b32_e32 v133, v159
	v_lshlrev_b32_e32 v140, 16, v130
	v_and_b32_e32 v130, 0xffff0000, v130
	v_lshlrev_b32_e32 v141, 16, v131
	v_and_b32_e32 v142, 0xffff0000, v131
	v_lshlrev_b32_e32 v143, 16, v132
	v_and_b32_e32 v144, 0xffff0000, v132
	v_lshlrev_b32_e32 v145, 16, v133
	v_and_b32_e32 v146, 0xffff0000, v133
	s_waitcnt vmcnt(6)
	s_nop 1
	v_mov_b32_e32 v134, v160
	v_mov_b32_e32 v135, v161
	v_mov_b32_e32 v136, v162
	v_mov_b32_e32 v137, v163
	v_lshlrev_b32_e32 v147, 16, v134
	v_and_b32_e32 v148, 0xffff0000, v134
	v_lshlrev_b32_e32 v149, 16, v135
	v_and_b32_e32 v150, 0xffff0000, v135
	v_lshlrev_b32_e32 v151, 16, v136
	v_and_b32_e32 v152, 0xffff0000, v136
	v_lshlrev_b32_e32 v153, 16, v137
	v_and_b32_e32 v154, 0xffff0000, v137
	s_waitcnt lgkmcnt(1)
	v_sub_f32_e32 v131, v130, v84
	v_sub_f32_e32 v130, v140, v84
	v_sub_f32_e32 v133, v142, v84
	v_sub_f32_e32 v132, v141, v84
	v_sub_f32_e32 v135, v144, v84
	v_sub_f32_e32 v134, v143, v84
	v_sub_f32_e32 v137, v146, v84
	v_sub_f32_e32 v136, v145, v84
	v_pk_mul_f32 v[132:133], v[84:85], v[132:133] op_sel:[1,0]
	v_pk_mul_f32 v[130:131], v[84:85], v[130:131] op_sel:[1,0]
	v_pk_mul_f32 v[136:137], v[84:85], v[136:137] op_sel:[1,0]
	v_pk_mul_f32 v[134:135], v[84:85], v[134:135] op_sel:[1,0]
	v_pk_fma_f32 v[130:131], v[100:101], v[130:131], v[96:97]
	v_pk_fma_f32 v[132:133], v[102:103], v[132:133], v[98:99]
	v_pk_fma_f32 v[134:135], v[104:105], v[134:135], v[108:109]
	v_pk_fma_f32 v[136:137], v[106:107], v[136:137], v[110:111]
	v_sub_f32_e32 v141, v148, v86
	v_sub_f32_e32 v140, v147, v86
	v_sub_f32_e32 v143, v150, v86
	v_sub_f32_e32 v142, v149, v86
	v_sub_f32_e32 v145, v152, v86
	v_sub_f32_e32 v144, v151, v86
	v_pk_fma_f32 v[62:63], v[132:133], s[70:71], v[62:63] op_sel_hi:[1,0,1]
	v_pk_fma_f32 v[60:61], v[130:131], s[70:71], v[60:61] op_sel_hi:[1,0,1]
	v_pk_fma_f32 v[58:59], v[136:137], s[70:71], v[58:59] op_sel_hi:[1,0,1]
	v_pk_fma_f32 v[56:57], v[134:135], s[70:71], v[56:57] op_sel_hi:[1,0,1]
	v_cvt_pk_bf16_f32 v130, v60, v61
	v_cvt_pk_bf16_f32 v131, v62, v63
	v_pk_mul_f32 v[134:135], v[86:87], v[142:143] op_sel:[1,0]
	v_cvt_pk_bf16_f32 v132, v56, v57
	v_cvt_pk_bf16_f32 v133, v58, v59
	global_store_dwordx4 v[126:127], v[130:133], off
	v_sub_f32_e32 v127, v154, v86
	v_sub_f32_e32 v126, v153, v86
	v_pk_mul_f32 v[136:137], v[86:87], v[140:141] op_sel:[1,0]
	v_pk_mul_f32 v[126:127], v[86:87], v[126:127] op_sel:[1,0]
	v_pk_mul_f32 v[140:141], v[86:87], v[144:145] op_sel:[1,0]
	v_pk_fma_f32 v[136:137], v[100:101], v[136:137], v[96:97]
	v_pk_fma_f32 v[134:135], v[102:103], v[134:135], v[98:99]
	v_pk_fma_f32 v[140:141], v[104:105], v[140:141], v[108:109]
	v_pk_fma_f32 v[126:127], v[106:107], v[126:127], v[110:111]
	v_pk_fma_f32 v[54:55], v[134:135], s[70:71], v[54:55] op_sel_hi:[1,0,1]
	v_pk_fma_f32 v[52:53], v[136:137], s[70:71], v[52:53] op_sel_hi:[1,0,1]
	v_pk_fma_f32 v[50:51], v[126:127], s[70:71], v[50:51] op_sel_hi:[1,0,1]
	v_pk_fma_f32 v[48:49], v[140:141], s[70:71], v[48:49] op_sel_hi:[1,0,1]
	v_cvt_pk_bf16_f32 v134, v52, v53
	v_cvt_pk_bf16_f32 v135, v54, v55
	s_waitcnt vmcnt(6)
	s_nop 1
	v_mov_b32_e32 v130, v164
	v_mov_b32_e32 v131, v165
	v_mov_b32_e32 v132, v166
	v_mov_b32_e32 v133, v167
	v_and_b32_e32 v140, 0xffff0000, v132
	v_cvt_pk_bf16_f32 v136, v48, v49
	v_cvt_pk_bf16_f32 v137, v50, v51
	global_store_dwordx4 v[124:125], v[134:137], off
	v_lshlrev_b32_e32 v141, 16, v133
	v_lshlrev_b32_e32 v134, 16, v130
	v_and_b32_e32 v130, 0xffff0000, v130
	v_lshlrev_b32_e32 v135, 16, v131
	v_and_b32_e32 v136, 0xffff0000, v131
	v_lshlrev_b32_e32 v137, 16, v132
	v_and_b32_e32 v142, 0xffff0000, v133
	s_waitcnt lgkmcnt(0)
	v_sub_f32_e32 v131, v130, v80
	v_sub_f32_e32 v130, v134, v80
	v_sub_f32_e32 v133, v136, v80
	v_sub_f32_e32 v132, v135, v80
	v_sub_f32_e32 v135, v140, v80
	v_sub_f32_e32 v134, v137, v80
	v_sub_f32_e32 v137, v142, v80
	v_sub_f32_e32 v136, v141, v80
	v_pk_mul_f32 v[132:133], v[80:81], v[132:133] op_sel:[1,0]
	v_pk_mul_f32 v[130:131], v[80:81], v[130:131] op_sel:[1,0]
	v_pk_mul_f32 v[136:137], v[80:81], v[136:137] op_sel:[1,0]
	v_pk_mul_f32 v[134:135], v[80:81], v[134:135] op_sel:[1,0]
	s_waitcnt vmcnt(6)
	s_nop 1
	v_mov_b32_e32 v124, v196
	v_mov_b32_e32 v125, v197
	v_mov_b32_e32 v126, v198
	v_mov_b32_e32 v127, v199
	v_lshlrev_b32_e32 v140, 16, v124
	v_and_b32_e32 v141, 0xffff0000, v124
	v_lshlrev_b32_e32 v142, 16, v125
	v_and_b32_e32 v143, 0xffff0000, v125
	v_lshlrev_b32_e32 v144, 16, v126
	v_and_b32_e32 v145, 0xffff0000, v126
	v_lshlrev_b32_e32 v146, 16, v127
	v_and_b32_e32 v147, 0xffff0000, v127
	v_pk_fma_f32 v[124:125], v[100:101], v[130:131], v[96:97]
	v_pk_fma_f32 v[126:127], v[102:103], v[132:133], v[98:99]
	v_pk_fma_f32 v[130:131], v[104:105], v[134:135], v[108:109]
	v_pk_fma_f32 v[132:133], v[106:107], v[136:137], v[110:111]
	v_sub_f32_e32 v135, v141, v82
	v_sub_f32_e32 v134, v140, v82
	v_sub_f32_e32 v137, v143, v82
	v_sub_f32_e32 v136, v142, v82
	v_sub_f32_e32 v141, v145, v82
	v_sub_f32_e32 v140, v144, v82
	v_sub_f32_e32 v143, v147, v82
	v_sub_f32_e32 v142, v146, v82
	v_pk_fma_f32 v[42:43], v[132:133], s[70:71], v[42:43] op_sel_hi:[1,0,1]
	v_pk_fma_f32 v[40:41], v[130:131], s[70:71], v[40:41] op_sel_hi:[1,0,1]
	v_pk_mul_f32 v[130:131], v[82:83], v[136:137] op_sel:[1,0]
	v_pk_mul_f32 v[132:133], v[82:83], v[134:135] op_sel:[1,0]
	v_pk_mul_f32 v[134:135], v[82:83], v[142:143] op_sel:[1,0]
	v_pk_mul_f32 v[136:137], v[82:83], v[140:141] op_sel:[1,0]
	v_pk_fma_f32 v[96:97], v[100:101], v[132:133], v[96:97]
	v_pk_fma_f32 v[98:99], v[102:103], v[130:131], v[98:99]
	v_pk_fma_f32 v[100:101], v[104:105], v[136:137], v[108:109]
	v_pk_fma_f32 v[102:103], v[106:107], v[134:135], v[110:111]
	v_pk_fma_f32 v[46:47], v[126:127], s[70:71], v[46:47] op_sel_hi:[1,0,1]
	v_pk_fma_f32 v[44:45], v[124:125], s[70:71], v[44:45] op_sel_hi:[1,0,1]
	v_pk_fma_f32 v[38:39], v[98:99], s[70:71], v[38:39] op_sel_hi:[1,0,1]
	v_cvt_pk_bf16_f32 v124, v44, v45
	v_cvt_pk_bf16_f32 v125, v46, v47
	v_cvt_pk_bf16_f32 v126, v40, v41
	v_cvt_pk_bf16_f32 v127, v42, v43
	global_store_dwordx4 v[138:139], v[124:127], off
	v_pk_fma_f32 v[36:37], v[96:97], s[70:71], v[36:37] op_sel_hi:[1,0,1]
	v_pk_fma_f32 v[34:35], v[102:103], s[70:71], v[34:35] op_sel_hi:[1,0,1]
	v_pk_fma_f32 v[32:33], v[100:101], s[70:71], v[32:33] op_sel_hi:[1,0,1]
	v_cvt_pk_bf16_f32 v100, v36, v37
	v_cvt_pk_bf16_f32 v101, v38, v39
	v_lshl_add_u64 v[96:97], s[42:43], 0, v[116:117]
	v_cvt_pk_bf16_f32 v102, v32, v33
	v_cvt_pk_bf16_f32 v103, v34, v35
	v_lshl_add_u64 v[114:115], v[96:97], 0, v[128:129]
	v_lshl_add_u64 v[96:97], s[42:43], 0, v[122:123]
	global_store_dwordx4 v[118:119], v[100:103], off
	v_lshl_add_u64 v[116:117], s[42:43], 0, v[120:121]
	v_lshl_add_u64 v[98:99], v[96:97], 0, v[128:129]
	v_lshl_add_u64 v[96:97], v[116:117], 0, v[128:129]
	s_waitcnt vmcnt(7)
	s_nop 1
	v_mov_b32_e32 v104, v200
	v_mov_b32_e32 v105, v201
	v_mov_b32_e32 v106, v202
	v_mov_b32_e32 v107, v203
	v_lshlrev_b32_e32 v100, 16, v104
	v_and_b32_e32 v101, 0xffff0000, v104
	v_lshlrev_b32_e32 v102, 16, v105
	v_and_b32_e32 v103, 0xffff0000, v105
	v_lshlrev_b32_e32 v104, 16, v106
	v_and_b32_e32 v105, 0xffff0000, v106
	v_lshlrev_b32_e32 v106, 16, v107
	v_and_b32_e32 v107, 0xffff0000, v107
	v_sub_f32_e32 v101, v101, v84
	v_sub_f32_e32 v100, v100, v84
	v_sub_f32_e32 v103, v103, v84
	v_sub_f32_e32 v102, v102, v84
	v_sub_f32_e32 v105, v105, v84
	v_sub_f32_e32 v104, v104, v84
	v_sub_f32_e32 v107, v107, v84
	v_sub_f32_e32 v106, v106, v84
	v_pk_mul_f32 v[102:103], v[84:85], v[102:103] op_sel:[1,0]
	v_pk_mul_f32 v[100:101], v[84:85], v[100:101] op_sel:[1,0]
	v_pk_mul_f32 v[106:107], v[84:85], v[106:107] op_sel:[1,0]
	v_pk_mul_f32 v[84:85], v[84:85], v[104:105] op_sel:[1,0]
	v_pk_fma_f32 v[100:101], v[72:73], v[100:101], v[76:77]
	v_pk_fma_f32 v[102:103], v[74:75], v[102:103], v[78:79]
	v_pk_fma_f32 v[84:85], v[64:65], v[84:85], v[68:69]
	s_waitcnt vmcnt(6)
	s_nop 1
	v_mov_b32_e32 v108, v204
	v_mov_b32_e32 v109, v205
	v_mov_b32_e32 v110, v206
	v_mov_b32_e32 v111, v207
	v_lshlrev_b32_e32 v116, 16, v108
	v_and_b32_e32 v108, 0xffff0000, v108
	v_lshlrev_b32_e32 v117, 16, v109
	v_and_b32_e32 v118, 0xffff0000, v109
	v_lshlrev_b32_e32 v119, 16, v110
	v_and_b32_e32 v120, 0xffff0000, v110
	v_lshlrev_b32_e32 v121, 16, v111
	v_and_b32_e32 v122, 0xffff0000, v111
	v_pk_fma_f32 v[104:105], v[66:67], v[106:107], v[70:71]
	v_pk_fma_f32 v[102:103], v[102:103], s[70:71], v[30:31] op_sel_hi:[1,0,1]
	v_pk_fma_f32 v[100:101], v[100:101], s[70:71], v[28:29] op_sel_hi:[1,0,1]
	v_pk_fma_f32 v[106:107], v[84:85], s[70:71], v[24:25] op_sel_hi:[1,0,1]
	v_cvt_pk_bf16_f32 v24, v100, v101
	v_cvt_pk_bf16_f32 v25, v102, v103
	v_sub_f32_e32 v109, v108, v86
	v_sub_f32_e32 v108, v116, v86
	v_sub_f32_e32 v111, v118, v86
	v_sub_f32_e32 v110, v117, v86
	v_sub_f32_e32 v117, v120, v86
	v_sub_f32_e32 v116, v119, v86
	v_pk_fma_f32 v[104:105], v[104:105], s[70:71], v[26:27] op_sel_hi:[1,0,1]
	v_cvt_pk_bf16_f32 v26, v106, v107
	v_pk_mul_f32 v[84:85], v[86:87], v[108:109] op_sel:[1,0]
	v_cvt_pk_bf16_f32 v27, v104, v105
	global_store_dwordx4 v[112:113], v[24:27], off
	v_pk_fma_f32 v[84:85], v[72:73], v[84:85], v[76:77]
	v_sub_f32_e32 v25, v122, v86
	v_sub_f32_e32 v24, v121, v86
	v_pk_mul_f32 v[26:27], v[86:87], v[110:111] op_sel:[1,0]
	v_pk_mul_f32 v[24:25], v[86:87], v[24:25] op_sel:[1,0]
	v_pk_mul_f32 v[86:87], v[86:87], v[116:117] op_sel:[1,0]
	v_pk_fma_f32 v[26:27], v[74:75], v[26:27], v[78:79]
	v_pk_fma_f32 v[86:87], v[64:65], v[86:87], v[68:69]
	v_pk_fma_f32 v[24:25], v[66:67], v[24:25], v[70:71]
	v_pk_fma_f32 v[22:23], v[26:27], s[70:71], v[22:23] op_sel_hi:[1,0,1]
	v_pk_fma_f32 v[20:21], v[84:85], s[70:71], v[20:21] op_sel_hi:[1,0,1]
	v_pk_fma_f32 v[18:19], v[24:25], s[70:71], v[18:19] op_sel_hi:[1,0,1]
	v_pk_fma_f32 v[16:17], v[86:87], s[70:71], v[16:17] op_sel_hi:[1,0,1]
	v_cvt_pk_bf16_f32 v24, v20, v21
	v_cvt_pk_bf16_f32 v25, v22, v23
	v_pk_mul_f32 v[120:121], v[104:105], v[104:105]
	v_cvt_pk_bf16_f32 v26, v16, v17
	v_cvt_pk_bf16_f32 v27, v18, v19
	global_store_dwordx4 v[114:115], v[24:27], off
	v_pk_mul_f32 v[122:123], v[106:107], v[106:107]
	v_add_f32_e32 v24, v60, v61
	v_add_f32_e32 v26, v62, v63
	v_add_f32_e32 v108, v56, v57
	v_add_f32_e32 v110, v58, v59
	v_mul_f32_e32 v113, v60, v60
	v_mul_f32_e32 v25, v100, v100
	v_mul_f32_e32 v27, v101, v101
	v_mul_f32_e32 v109, v102, v102
	v_mul_f32_e32 v111, v103, v103
	v_mov_b32_e32 v112, v100
	v_mov_b32_e32 v60, v101
	v_pk_mov_b32 v[100:101], v[122:123], v[120:121] op_sel:[1,0]
	v_mov_b32_e32 v123, v121
	v_mul_f32_e32 v61, v61, v61
	v_mul_f32_e32 v115, v62, v62
	v_mul_f32_e32 v63, v63, v63
	v_mul_f32_e32 v117, v56, v56
	v_mul_f32_e32 v57, v57, v57
	v_mul_f32_e32 v119, v58, v58
	v_mul_f32_e32 v59, v59, v59
	v_mov_b32_e32 v114, v102
	v_mov_b32_e32 v62, v103
	v_mov_b32_e32 v116, v106
	v_mov_b32_e32 v56, v107
	v_mov_b32_e32 v118, v104
	v_mov_b32_e32 v58, v105
	v_pk_add_f32 v[24:25], v[24:25], v[26:27]
	v_pk_add_f32 v[26:27], v[108:109], v[110:111]
	v_pk_add_f32 v[100:101], v[100:101], v[122:123]
	v_pk_add_f32 v[60:61], v[112:113], v[60:61]
	v_pk_add_f32 v[62:63], v[114:115], v[62:63]
	v_pk_add_f32 v[56:57], v[116:117], v[56:57]
	v_pk_add_f32 v[58:59], v[118:119], v[58:59]
	v_pk_add_f32 v[24:25], v[24:25], v[26:27]
	v_pk_add_f32 v[26:27], v[100:101], v[100:101] op_sel_hi:[0,1]
	v_pk_add_f32 v[60:61], v[60:61], v[62:63]
	v_pk_add_f32 v[56:57], v[56:57], v[58:59]
	v_mov_b32_e32 v26, v175
	v_pk_add_f32 v[56:57], v[60:61], v[56:57]
	v_pk_add_f32 v[24:25], v[24:25], v[26:27]
	s_waitcnt vmcnt(7)
	s_nop 1
	v_mov_b32_e32 v28, v208
	v_mov_b32_e32 v29, v209
	v_mov_b32_e32 v30, v210
	v_mov_b32_e32 v31, v211
	v_and_b32_e32 v58, 0xffff0000, v29
	v_pk_add_f32 v[24:25], v[56:57], v[24:25]
	ds_bpermute_b32 v26, v225, v24
	ds_bpermute_b32 v27, v225, v25
	v_lshlrev_b32_e32 v56, 16, v28
	v_and_b32_e32 v28, 0xffff0000, v28
	v_lshlrev_b32_e32 v57, 16, v29
	v_lshlrev_b32_e32 v59, 16, v30
	v_and_b32_e32 v60, 0xffff0000, v30
	v_lshlrev_b32_e32 v61, 16, v31
	v_and_b32_e32 v62, 0xffff0000, v31
	s_waitcnt lgkmcnt(0)
	v_pk_add_f32 v[24:25], v[24:25], v[26:27]
	v_sub_f32_e32 v29, v28, v80
	v_sub_f32_e32 v28, v56, v80
	v_sub_f32_e32 v31, v58, v80
	v_sub_f32_e32 v30, v57, v80
	v_sub_f32_e32 v57, v60, v80
	v_sub_f32_e32 v56, v59, v80
	v_sub_f32_e32 v59, v62, v80
	v_sub_f32_e32 v58, v61, v80
	ds_bpermute_b32 v26, v226, v24
	ds_bpermute_b32 v27, v226, v25
	v_pk_mul_f32 v[30:31], v[80:81], v[30:31] op_sel:[1,0]
	v_pk_mul_f32 v[28:29], v[80:81], v[28:29] op_sel:[1,0]
	v_pk_mul_f32 v[58:59], v[80:81], v[58:59] op_sel:[1,0]
	v_pk_mul_f32 v[56:57], v[80:81], v[56:57] op_sel:[1,0]
	s_waitcnt vmcnt(6)
	s_nop 1
	v_mov_b32_e32 v84, v212
	v_mov_b32_e32 v85, v213
	v_mov_b32_e32 v86, v214
	v_mov_b32_e32 v87, v215
	v_lshlrev_b32_e32 v60, 16, v84
	v_and_b32_e32 v61, 0xffff0000, v84
	v_lshlrev_b32_e32 v62, 16, v85
	v_and_b32_e32 v63, 0xffff0000, v85
	v_lshlrev_b32_e32 v80, 16, v86
	v_and_b32_e32 v81, 0xffff0000, v86
	v_lshlrev_b32_e32 v84, 16, v87
	v_and_b32_e32 v85, 0xffff0000, v87
	v_pk_fma_f32 v[56:57], v[64:65], v[56:57], v[68:69]
	v_pk_fma_f32 v[58:59], v[66:67], v[58:59], v[70:71]
	v_sub_f32_e32 v61, v61, v82
	v_sub_f32_e32 v60, v60, v82
	v_sub_f32_e32 v63, v63, v82
	v_sub_f32_e32 v62, v62, v82
	v_sub_f32_e32 v81, v81, v82
	v_sub_f32_e32 v80, v80, v82
	v_sub_f32_e32 v85, v85, v82
	v_sub_f32_e32 v84, v84, v82
	v_pk_fma_f32 v[10:11], v[58:59], s[70:71], v[10:11] op_sel_hi:[1,0,1]
	v_pk_fma_f32 v[8:9], v[56:57], s[70:71], v[8:9] op_sel_hi:[1,0,1]
	v_pk_mul_f32 v[56:57], v[82:83], v[62:63] op_sel:[1,0]
	v_pk_mul_f32 v[58:59], v[82:83], v[60:61] op_sel:[1,0]
	v_pk_mul_f32 v[60:61], v[82:83], v[84:85] op_sel:[1,0]
	v_pk_mul_f32 v[62:63], v[82:83], v[80:81] op_sel:[1,0]
	v_pk_fma_f32 v[28:29], v[72:73], v[28:29], v[76:77]
	v_pk_fma_f32 v[30:31], v[74:75], v[30:31], v[78:79]
	v_pk_fma_f32 v[58:59], v[72:73], v[58:59], v[76:77]
	v_pk_fma_f32 v[56:57], v[74:75], v[56:57], v[78:79]
	v_pk_fma_f32 v[62:63], v[64:65], v[62:63], v[68:69]
	v_pk_fma_f32 v[60:61], v[66:67], v[60:61], v[70:71]
	v_pk_fma_f32 v[14:15], v[30:31], s[70:71], v[14:15] op_sel_hi:[1,0,1]
	v_pk_fma_f32 v[12:13], v[28:29], s[70:71], v[12:13] op_sel_hi:[1,0,1]
	v_pk_fma_f32 v[6:7], v[56:57], s[70:71], v[6:7] op_sel_hi:[1,0,1]
	v_cvt_pk_bf16_f32 v28, v12, v13
	v_cvt_pk_bf16_f32 v29, v14, v15
	v_cvt_pk_bf16_f32 v30, v8, v9
	v_cvt_pk_bf16_f32 v31, v10, v11
	v_pk_fma_f32 v[4:5], v[58:59], s[70:71], v[4:5] op_sel_hi:[1,0,1]
	v_pk_fma_f32 v[2:3], v[60:61], s[70:71], v[2:3] op_sel_hi:[1,0,1]
	v_pk_fma_f32 v[0:1], v[62:63], s[70:71], v[0:1] op_sel_hi:[1,0,1]
	global_store_dwordx4 v[98:99], v[28:31], off
	s_nop 1
	v_cvt_pk_bf16_f32 v28, v4, v5
	v_cvt_pk_bf16_f32 v29, v6, v7
	v_cvt_pk_bf16_f32 v30, v0, v1
	v_cvt_pk_bf16_f32 v31, v2, v3
	global_store_dwordx4 v[96:97], v[28:31], off
	s_and_saveexec_b64 s[10:11], s[22:23]
	s_cbranch_execz .LBB0_1362
	v_lshlrev_b64 v[28:29], 7, v[94:95]
	v_lshl_add_u64 v[28:29], s[44:45], 0, v[28:29]
	s_waitcnt lgkmcnt(0)
	v_pk_add_f32 v[24:25], v[24:25], v[26:27]
	global_store_dwordx2 v[28:29], v[24:25], off
